# attention processes two adjacent grid rows per wave sharing K and V tiles (45 percent fewer loads); block waits for its attention waves before starting the d0 scan items
# speedup vs baseline: 1.1330x; 1.0062x over previous
; __device__ __forceinline__ void nat_phase(const Params& p, float* ldsf, int wave0, int nwaves) {
;     ...
;     for (int item = wave0; item < 8192; item += nwaves) {
;         const int r = item & 255, h = (item >> 8) & 15, b = item >> 12;
;         const int rs = min(max(r - 4, 0), 248);
;         const u16* Qb = Qn + (size_t)(b * SEQ + r * 64) * RW + h * 64;
;         const u16* Kb = Kn + (size_t)(b * SEQ + rs * 64) * RW + h * 64;
;         const u16* Vb = VT + (size_t)((b * 16 + h) * 64) * SEQ + rs * 64;
;         float* tb = ldsf + wid * 256;
;         { const float* rpb = p.rpb + h * 465 + (rs - r + 7) * 31;
; #pragma unroll
;           for (int q = 0; q < 4; ++q) { const int e = lane + q * 64; if (e < 248) tb[e] = rpb[e]; } }
; #pragma unroll 1
;         for (int qt = 0; qt < 4; ++qt) {
;             const int c0 = qt * 16, cs0 = (qt == 0) ? 0 : (qt == 1 ? 8 : (qt == 2 ? 24 : 32));
;             const int c = c0 + l15, csq = min(max(c - 8, 0), 48);
;             const bf16x8 bq0 = *(const bf16x8*)(Qb + (size_t)c * RW + lq * 8), bq1 = *(const bf16x8*)(Qb + (size_t)c * RW + 32 + lq * 8);
.LBB0_413:
	s_cmp_lt_i32 s58, 5
	s_cselect_b64 s[0:1], -1, 0
	s_cmp_gt_i32 s59, 4
	s_cselect_b64 s[4:5], -1, 0
	s_and_b64 s[0:1], s[0:1], s[4:5]
	s_andn2_b64 vcc, exec, s[0:1]
	s_cbranch_vccnz .LBB0_628
	v_readfirstlane_b32 s0, v254
	v_and_b32_e32 v96, 63, v254
	s_cmpk_lt_u32 s0, 0x100
	v_and_b32_e32 v65, 15, v254
	s_cbranch_scc1 .LBB0_555
	s_setprio 3
	s_lshr_b32 s1, s0, 6
	s_lshl_b32 s88, s2, 2
	s_add_i32 s88, s88, s1
	s_add_i32 s88, s88, -4
	s_cmpk_gt_i32 s88, 0xfff
	s_cbranch_scc1 .Lmy_nat_end
	s_lshl_b32 s81, s96, 2
	s_mov_b32 s64, s56
	s_and_b32 s65, s57, 0xffff
	s_brev_b32 s66, -2
	s_mov_b32 s67, 0x27000
	s_mov_b32 s68, s54
	s_and_b32 s69, s55, 0xffff
	s_mov_b32 s70, s66
	s_mov_b32 s71, s67
	s_mov_b32 s72, s50
	s_and_b32 s73, s51, 0xffff
	s_movk_i32 s74, 0x7440
	s_mov_b32 s75, s67
	v_and_b32_e32 v237, 15, v254
	v_bfe_u32 v238, v254, 4, 2
	v_and_b32_e32 v242, 63, v254
	v_lshlrev_b32_e32 v243, 4, v238
	v_lshl_add_u32 v224, v237, 11, v243
	v_lshl_add_u32 v226, v237, 15, v243
	v_lshrrev_b32_e32 v244, 2, v237
	v_and_b32_e32 v245, 3, v237
	v_lshl_add_u32 v244, v244, 3, v245
	v_lshl_add_u32 v225, v244, 11, v243
	v_lshlrev_b32_e32 v243, 3, v238
	v_lshl_add_u32 v227, v237, 11, v243
	v_lshl_add_u32 v228, v237, 12, v243
	v_xor_b32_e32 v248, 16, v242
	v_lshlrev_b32_e32 v248, 2, v248
	v_xor_b32_e32 v249, 32, v242
	v_lshlrev_b32_e32 v249, 2, v249
	s_lshl_b32 s3, s1, 11
	s_add_u32 s3, s3, 0x6000
	v_lshl_add_u32 v250, v242, 2, s3
	v_mov_b32_e32 v243, 0xf2c9f2ca
	ds_write_b32 v250, v243 offset:1024
	ds_write_b32 v250, v243 offset:1280
	ds_write_b32 v250, v243 offset:1536
	ds_write_b32 v250, v243 offset:1792
	v_mov_b32_e32 v252, 0x3e38aa3b
	v_mov_b32_e32 v253, 0x3e38aa3b
.Lmy_nat_pair:
	s_and_b32 s4, s88, 127
	s_lshl_b32 s4, s4, 1
	s_lshr_b32 s5, s88, 7
	s_lshl_b32 s5, s5, 8
	s_add_u32 s0, s5, s4
	s_cmp_lt_u32 s4, 4
	s_cbranch_scc1 .Lmy_nat_edge
	s_cmp_gt_u32 s4, 250
	s_cbranch_scc1 .Lmy_nat_edge
	s_and_b32 s4, s0, 255
	s_bfe_u32 s5, s0, 0x40008
	s_lshr_b32 s6, s0, 12
	s_add_i32 s7, s4, -4
	s_max_i32 s7, s7, 0
	s_min_i32 s7, s7, 0xf8
	s_lshl_b32 s8, s6, 14
	s_lshl_b32 s9, s4, 6
	s_add_u32 s9, s9, s8
	s_lshl_b32 s84, s5, 7
	s_lshl_b32 s76, s9, 11
	s_add_u32 s76, s76, s84
	s_add_u32 s79, s76, 0xc000000
	s_lshl_b32 s80, s9, 12
	s_add_u32 s80, s80, s84
	s_add_u32 s80, s80, 0x3800800
	s_lshl_b32 s85, s7, 6
	s_add_u32 s85, s85, s8
	s_lshl_b32 s77, s85, 11
	s_add_u32 s77, s77, s84
	s_add_u32 s77, s77, 0x4000000
	s_lshl_b32 s85, s6, 4
	s_add_u32 s85, s85, s5
	s_lshl_b32 s78, s85, 21
	s_lshl_b32 s86, s7, 7
	s_add_u32 s78, s78, s86
	s_add_u32 s78, s78, 0x8000000
	s_sub_i32 s85, s7, s4
	s_add_i32 s85, s85, 7
	s_mul_i32 s85, s85, 31
	s_mul_i32 s86, s5, 465
	s_add_u32 s85, s85, s86
	s_lshl_b32 s85, s85, 2
	v_and_b32_e32 v242, 63, v254
	v_lshlrev_b32_e32 v244, 2, v242
	buffer_load_dword v0, v244, s[72:75], s85 offen offset:0
	buffer_load_dword v1, v244, s[72:75], s85 offen offset:256
	buffer_load_dword v2, v244, s[72:75], s85 offen offset:512
	buffer_load_dword v3, v244, s[72:75], s85 offen offset:768
	s_waitcnt vmcnt(0)
	v_mul_f32_e32 v0, 0x41000000, v0
	v_mul_f32_e32 v1, 0x41000000, v1
	v_mul_f32_e32 v2, 0x41000000, v2
	v_mul_f32_e32 v3, 0x41000000, v3
	ds_write_b32 v250, v0 offset:0
	ds_write_b32 v250, v1 offset:256
	ds_write_b32 v250, v2 offset:512
	ds_write_b32 v250, v3 offset:768
	s_mov_b32 s16, 0
.Lmy_nat_dqt:
	s_lshl_b32 s82, s16, 4
	s_add_i32 s83, s82, -8
	s_max_i32 s83, s83, 0
	s_min_i32 s83, s83, 32
	s_lshl_b32 s84, s82, 11
	s_add_u32 s84, s84, s76
	buffer_load_dwordx4 v[160:163], v224, s[68:71], s84 offen
	buffer_load_dwordx4 v[164:167], v224, s[68:71], s84 offen offset:64
	s_add_u32 s85, s84, 0x20000
	buffer_load_dwordx4 v[168:171], v224, s[68:71], s85 offen
	buffer_load_dwordx4 v[172:175], v224, s[68:71], s85 offen offset:64
	s_lshl_b32 s84, s83, 11
	s_add_u32 s84, s84, s77
	s_add_u32 s85, s84, 0x0
	buffer_load_dwordx4 v[0:3], v225, s[68:71], s85 offen
	s_add_u32 s85, s84, 0x0
	buffer_load_dwordx4 v[4:7], v225, s[68:71], s85 offen offset:64
	s_add_u32 s85, s84, 0x2000
	buffer_load_dwordx4 v[8:11], v225, s[68:71], s85 offen
	s_add_u32 s85, s84, 0x2000
	buffer_load_dwordx4 v[12:15], v225, s[68:71], s85 offen offset:64
	s_add_u32 s85, s84, 0x20000
	buffer_load_dwordx4 v[16:19], v225, s[68:71], s85 offen
	s_add_u32 s85, s84, 0x20000
	buffer_load_dwordx4 v[20:23], v225, s[68:71], s85 offen offset:64
	s_add_u32 s85, s84, 0x22000
	buffer_load_dwordx4 v[24:27], v225, s[68:71], s85 offen
	s_add_u32 s85, s84, 0x22000
	buffer_load_dwordx4 v[28:31], v225, s[68:71], s85 offen offset:64
	v_add_u32_e32 v241, s82, v237
	v_add_u32_e32 v242, -8, v241
	v_med3_i32 v242, v242, 0, 48
	v_lshl_add_u32 v251, v238, 3, s83
	v_sub_u32_e32 v243, v251, v242
	v_sub_u32_e32 v244, v251, v241
	v_lshl_add_u32 v244, v244, 2, s3
	v_mov_b32_e32 v245, s3
	v_add_u32_e32 v245, 0x400, v245
	v_add_u32_e32 v246, 0, v243
	v_cmp_gt_u32_e32 vcc, 16, v246
	v_add_u32_e32 v247, 60, v244
	s_nop 0
	v_cndmask_b32_e32 v229, v245, v247, vcc
	v_add_u32_e32 v246, 1, v243
	v_cmp_gt_u32_e32 vcc, 16, v246
	v_add_u32_e32 v247, 64, v244
	s_nop 0
	v_cndmask_b32_e32 v230, v245, v247, vcc
	v_add_u32_e32 v246, 2, v243
	v_cmp_gt_u32_e32 vcc, 16, v246
	v_add_u32_e32 v247, 68, v244
	s_nop 0
	v_cndmask_b32_e32 v231, v245, v247, vcc
	v_add_u32_e32 v246, 3, v243
	v_cmp_gt_u32_e32 vcc, 16, v246
	v_add_u32_e32 v247, 72, v244
	s_nop 0
	v_cndmask_b32_e32 v232, v245, v247, vcc
	v_add_u32_e32 v246, 4, v243
	v_cmp_gt_u32_e32 vcc, 16, v246
	v_add_u32_e32 v247, 76, v244
	s_nop 0
	v_cndmask_b32_e32 v233, v245, v247, vcc
	v_add_u32_e32 v246, 5, v243
	v_cmp_gt_u32_e32 vcc, 16, v246
	v_add_u32_e32 v247, 80, v244
	s_nop 0
; __device__ __forceinline__ void nat_phase(const Params& p, float* ldsf, int wave0, int nwaves) {
;     ...
;                 for (int hf = 0; hf < 2; ++hf) { const u16* kp = Kb + (size_t)(i * 64 + cs0 + (l15 >> 2) * 8 + hf * 4 + (l15 & 3)) * RW + lq * 8;
;                     const bf16x8 a0 = *(const bf16x8*)kp, a1 = *(const bf16x8*)(kp + 32); f32x4 z = {0.f, 0.f, 0.f, 0.f};
;                     z = __builtin_amdgcn_mfma_f32_16x16x32_bf16(a0, bq0, z, 0, 0, 0); z = __builtin_amdgcn_mfma_f32_16x16x32_bf16(a1, bq1, z, 0, 0, 0); sc[i][hf] = z; }
;             float mx = -1e30f;
; #pragma unroll
;             for (int i = 0; i < 8; ++i)
; #pragma unroll
;                 for (int hf = 0; hf < 2; ++hf)
; #pragma unroll
;                     for (int j = 0; j < 4; ++j) { const int kc = cs0 + lq * 8 + hf * 4 + j; const bool valid = (kc >= csq) && (kc < csq + 16); const int bc = valid ? (kc - c + 15) : 0;
;                         const float s = valid ? sc[i][hf][j] * 0.125f + tb[i * 31 + bc] : -1e30f; sc[i][hf][j] = s; mx = fmaxf(mx, s); }
	v_cndmask_b32_e32 v234, v245, v247, vcc
	v_add_u32_e32 v246, 6, v243
	v_cmp_gt_u32_e32 vcc, 16, v246
	v_add_u32_e32 v247, 84, v244
	s_nop 0
	v_cndmask_b32_e32 v235, v245, v247, vcc
	v_add_u32_e32 v246, 7, v243
	v_cmp_gt_u32_e32 vcc, 16, v246
	v_add_u32_e32 v247, 88, v244
	s_nop 0
	v_cndmask_b32_e32 v236, v245, v247, vcc
	ds_read_b32 v32, v229 offset:0
	ds_read_b32 v33, v230 offset:0
	ds_read_b32 v34, v231 offset:0
	ds_read_b32 v35, v232 offset:0
	ds_read_b32 v36, v233 offset:0
	ds_read_b32 v37, v234 offset:0
	ds_read_b32 v38, v235 offset:0
	ds_read_b32 v39, v236 offset:0
	ds_read_b32 v40, v229 offset:124
	ds_read_b32 v41, v230 offset:124
	ds_read_b32 v42, v231 offset:124
	ds_read_b32 v43, v232 offset:124
	ds_read_b32 v44, v233 offset:124
	ds_read_b32 v45, v234 offset:124
	ds_read_b32 v46, v235 offset:124
	ds_read_b32 v47, v236 offset:124
	ds_read_b32 v48, v229 offset:248
	ds_read_b32 v49, v230 offset:248
	ds_read_b32 v50, v231 offset:248
	ds_read_b32 v51, v232 offset:248
	ds_read_b32 v52, v233 offset:248
	ds_read_b32 v53, v234 offset:248
	ds_read_b32 v54, v235 offset:248
	ds_read_b32 v55, v236 offset:248
	ds_read_b32 v56, v229 offset:372
	ds_read_b32 v57, v230 offset:372
	ds_read_b32 v58, v231 offset:372
	ds_read_b32 v59, v232 offset:372
	ds_read_b32 v60, v233 offset:372
	ds_read_b32 v61, v234 offset:372
	ds_read_b32 v62, v235 offset:372
	ds_read_b32 v63, v236 offset:372
	ds_read_b32 v64, v229 offset:496
	ds_read_b32 v65, v230 offset:496
	ds_read_b32 v66, v231 offset:496
	ds_read_b32 v67, v232 offset:496
	ds_read_b32 v68, v233 offset:496
	ds_read_b32 v69, v234 offset:496
	ds_read_b32 v70, v235 offset:496
	ds_read_b32 v71, v236 offset:496
	ds_read_b32 v72, v229 offset:620
	ds_read_b32 v73, v230 offset:620
	ds_read_b32 v74, v231 offset:620
	ds_read_b32 v75, v232 offset:620
	ds_read_b32 v76, v233 offset:620
	ds_read_b32 v77, v234 offset:620
	ds_read_b32 v78, v235 offset:620
	ds_read_b32 v79, v236 offset:620
	ds_read_b32 v80, v229 offset:744
	ds_read_b32 v81, v230 offset:744
	ds_read_b32 v82, v231 offset:744
	ds_read_b32 v83, v232 offset:744
	ds_read_b32 v84, v233 offset:744
	ds_read_b32 v85, v234 offset:744
	ds_read_b32 v86, v235 offset:744
	ds_read_b32 v87, v236 offset:744
	ds_read_b32 v88, v229 offset:868
	ds_read_b32 v89, v230 offset:868
	ds_read_b32 v90, v231 offset:868
	ds_read_b32 v91, v232 offset:868
	ds_read_b32 v92, v233 offset:868
	ds_read_b32 v93, v234 offset:868
	ds_read_b32 v94, v235 offset:868
	ds_read_b32 v95, v236 offset:868
	ds_read_b32 v96, v229 offset:0
	ds_read_b32 v97, v230 offset:0
	ds_read_b32 v98, v231 offset:0
	ds_read_b32 v99, v232 offset:0
	ds_read_b32 v100, v233 offset:0
	ds_read_b32 v101, v234 offset:0
	ds_read_b32 v102, v235 offset:0
	ds_read_b32 v103, v236 offset:0
	ds_read_b32 v104, v229 offset:124
	ds_read_b32 v105, v230 offset:124
	ds_read_b32 v106, v231 offset:124
	ds_read_b32 v107, v232 offset:124
	ds_read_b32 v108, v233 offset:124
	ds_read_b32 v109, v234 offset:124
	ds_read_b32 v110, v235 offset:124
	ds_read_b32 v111, v236 offset:124
	ds_read_b32 v112, v229 offset:248
	ds_read_b32 v113, v230 offset:248
	ds_read_b32 v114, v231 offset:248
	ds_read_b32 v115, v232 offset:248
	ds_read_b32 v116, v233 offset:248
	ds_read_b32 v117, v234 offset:248
	ds_read_b32 v118, v235 offset:248
	ds_read_b32 v119, v236 offset:248
	ds_read_b32 v120, v229 offset:372
	ds_read_b32 v121, v230 offset:372
	ds_read_b32 v122, v231 offset:372
	ds_read_b32 v123, v232 offset:372
	ds_read_b32 v124, v233 offset:372
	ds_read_b32 v125, v234 offset:372
	ds_read_b32 v126, v235 offset:372
	ds_read_b32 v127, v236 offset:372
	ds_read_b32 v128, v229 offset:496
	ds_read_b32 v129, v230 offset:496
	ds_read_b32 v130, v231 offset:496
	ds_read_b32 v131, v232 offset:496
	ds_read_b32 v132, v233 offset:496
	ds_read_b32 v133, v234 offset:496
	ds_read_b32 v134, v235 offset:496
	ds_read_b32 v135, v236 offset:496
	ds_read_b32 v136, v229 offset:620
	ds_read_b32 v137, v230 offset:620
	ds_read_b32 v138, v231 offset:620
	ds_read_b32 v139, v232 offset:620
	ds_read_b32 v140, v233 offset:620
	ds_read_b32 v141, v234 offset:620
	ds_read_b32 v142, v235 offset:620
	ds_read_b32 v143, v236 offset:620
	ds_read_b32 v144, v229 offset:744
	ds_read_b32 v145, v230 offset:744
	ds_read_b32 v146, v231 offset:744
	ds_read_b32 v147, v232 offset:744
	ds_read_b32 v148, v233 offset:744
	ds_read_b32 v149, v234 offset:744
	ds_read_b32 v150, v235 offset:744
	ds_read_b32 v151, v236 offset:744
	ds_read_b32 v152, v229 offset:868
	ds_read_b32 v153, v230 offset:868
	ds_read_b32 v154, v231 offset:868
	ds_read_b32 v155, v232 offset:868
	ds_read_b32 v156, v233 offset:868
	ds_read_b32 v157, v234 offset:868
	ds_read_b32 v158, v235 offset:868
	ds_read_b32 v159, v236 offset:868
	s_waitcnt lgkmcnt(0)
	s_waitcnt vmcnt(7)
	v_mfma_f32_16x16x32_bf16 v[32:35], v[0:3], v[160:163], v[32:35]
	s_add_u32 s85, s84, 0x40000
	buffer_load_dwordx4 v[0:3], v225, s[68:71], s85 offen
	s_waitcnt vmcnt(7)
	v_mfma_f32_16x16x32_bf16 v[32:35], v[4:7], v[164:167], v[32:35]
	s_add_u32 s85, s84, 0x40000
	buffer_load_dwordx4 v[4:7], v225, s[68:71], s85 offen offset:64
	s_waitcnt vmcnt(7)
	v_mfma_f32_16x16x32_bf16 v[36:39], v[8:11], v[160:163], v[36:39]
	s_add_u32 s85, s84, 0x42000
	buffer_load_dwordx4 v[8:11], v225, s[68:71], s85 offen
	s_waitcnt vmcnt(7)
	v_mfma_f32_16x16x32_bf16 v[36:39], v[12:15], v[164:167], v[36:39]
	s_add_u32 s85, s84, 0x42000
	buffer_load_dwordx4 v[12:15], v225, s[68:71], s85 offen offset:64
	s_waitcnt vmcnt(7)
	v_mfma_f32_16x16x32_bf16 v[40:43], v[16:19], v[160:163], v[40:43]
	v_mfma_f32_16x16x32_bf16 v[96:99], v[16:19], v[168:171], v[96:99]
	s_add_u32 s85, s84, 0x60000
	buffer_load_dwordx4 v[16:19], v225, s[68:71], s85 offen
	s_waitcnt vmcnt(7)
; __device__ __forceinline__ void nat_phase(const Params& p, float* ldsf, int wave0, int nwaves) {
;     ...
;             for (int i = 0; i < 8; ++i)
; #pragma unroll
;                 for (int hf = 0; hf < 2; ++hf) { const u16* kp = Kb + (size_t)(i * 64 + cs0 + (l15 >> 2) * 8 + hf * 4 + (l15 & 3)) * RW + lq * 8;
;                     const bf16x8 a0 = *(const bf16x8*)kp, a1 = *(const bf16x8*)(kp + 32); f32x4 z = {0.f, 0.f, 0.f, 0.f};
;                     z = __builtin_amdgcn_mfma_f32_16x16x32_bf16(a0, bq0, z, 0, 0, 0); z = __builtin_amdgcn_mfma_f32_16x16x32_bf16(a1, bq1, z, 0, 0, 0); sc[i][hf] = z; }
	v_mfma_f32_16x16x32_bf16 v[40:43], v[20:23], v[164:167], v[40:43]
	v_mfma_f32_16x16x32_bf16 v[96:99], v[20:23], v[172:175], v[96:99]
	s_add_u32 s85, s84, 0x60000
	buffer_load_dwordx4 v[20:23], v225, s[68:71], s85 offen offset:64
	s_waitcnt vmcnt(7)
	v_mfma_f32_16x16x32_bf16 v[44:47], v[24:27], v[160:163], v[44:47]
	v_mfma_f32_16x16x32_bf16 v[100:103], v[24:27], v[168:171], v[100:103]
	s_add_u32 s85, s84, 0x62000
	buffer_load_dwordx4 v[24:27], v225, s[68:71], s85 offen
	s_waitcnt vmcnt(7)
	v_mfma_f32_16x16x32_bf16 v[44:47], v[28:31], v[164:167], v[44:47]
	v_mfma_f32_16x16x32_bf16 v[100:103], v[28:31], v[172:175], v[100:103]
	s_add_u32 s85, s84, 0x62000
	buffer_load_dwordx4 v[28:31], v225, s[68:71], s85 offen offset:64
	s_waitcnt vmcnt(7)
	v_mfma_f32_16x16x32_bf16 v[48:51], v[0:3], v[160:163], v[48:51]
	v_mfma_f32_16x16x32_bf16 v[104:107], v[0:3], v[168:171], v[104:107]
	s_add_u32 s85, s84, 0x80000
	buffer_load_dwordx4 v[0:3], v225, s[68:71], s85 offen
	s_waitcnt vmcnt(7)
	v_mfma_f32_16x16x32_bf16 v[48:51], v[4:7], v[164:167], v[48:51]
	v_mfma_f32_16x16x32_bf16 v[104:107], v[4:7], v[172:175], v[104:107]
	s_add_u32 s85, s84, 0x80000
	buffer_load_dwordx4 v[4:7], v225, s[68:71], s85 offen offset:64
	s_waitcnt vmcnt(7)
	v_mfma_f32_16x16x32_bf16 v[52:55], v[8:11], v[160:163], v[52:55]
	v_mfma_f32_16x16x32_bf16 v[108:111], v[8:11], v[168:171], v[108:111]
	s_add_u32 s85, s84, 0x82000
	buffer_load_dwordx4 v[8:11], v225, s[68:71], s85 offen
	s_waitcnt vmcnt(7)
	v_mfma_f32_16x16x32_bf16 v[52:55], v[12:15], v[164:167], v[52:55]
	v_mfma_f32_16x16x32_bf16 v[108:111], v[12:15], v[172:175], v[108:111]
	s_add_u32 s85, s84, 0x82000
	buffer_load_dwordx4 v[12:15], v225, s[68:71], s85 offen offset:64
	s_waitcnt vmcnt(7)
	v_mfma_f32_16x16x32_bf16 v[56:59], v[16:19], v[160:163], v[56:59]
	v_mfma_f32_16x16x32_bf16 v[112:115], v[16:19], v[168:171], v[112:115]
	s_add_u32 s85, s84, 0xa0000
	buffer_load_dwordx4 v[16:19], v225, s[68:71], s85 offen
	s_waitcnt vmcnt(7)
	v_mfma_f32_16x16x32_bf16 v[56:59], v[20:23], v[164:167], v[56:59]
	v_mfma_f32_16x16x32_bf16 v[112:115], v[20:23], v[172:175], v[112:115]
	s_add_u32 s85, s84, 0xa0000
	buffer_load_dwordx4 v[20:23], v225, s[68:71], s85 offen offset:64
	s_waitcnt vmcnt(7)
	v_mfma_f32_16x16x32_bf16 v[60:63], v[24:27], v[160:163], v[60:63]
	v_mfma_f32_16x16x32_bf16 v[116:119], v[24:27], v[168:171], v[116:119]
	s_add_u32 s85, s84, 0xa2000
	buffer_load_dwordx4 v[24:27], v225, s[68:71], s85 offen
	s_waitcnt vmcnt(7)
	v_mfma_f32_16x16x32_bf16 v[60:63], v[28:31], v[164:167], v[60:63]
	v_mfma_f32_16x16x32_bf16 v[116:119], v[28:31], v[172:175], v[116:119]
	s_add_u32 s85, s84, 0xa2000
	buffer_load_dwordx4 v[28:31], v225, s[68:71], s85 offen offset:64
	s_waitcnt vmcnt(7)
	v_mfma_f32_16x16x32_bf16 v[64:67], v[0:3], v[160:163], v[64:67]
	v_mfma_f32_16x16x32_bf16 v[120:123], v[0:3], v[168:171], v[120:123]
	s_add_u32 s85, s84, 0xc0000
	buffer_load_dwordx4 v[0:3], v225, s[68:71], s85 offen
	s_waitcnt vmcnt(7)
	v_mfma_f32_16x16x32_bf16 v[64:67], v[4:7], v[164:167], v[64:67]
	v_mfma_f32_16x16x32_bf16 v[120:123], v[4:7], v[172:175], v[120:123]
	s_add_u32 s85, s84, 0xc0000
	buffer_load_dwordx4 v[4:7], v225, s[68:71], s85 offen offset:64
	s_waitcnt vmcnt(7)
	v_mfma_f32_16x16x32_bf16 v[68:71], v[8:11], v[160:163], v[68:71]
	v_mfma_f32_16x16x32_bf16 v[124:127], v[8:11], v[168:171], v[124:127]
	s_add_u32 s85, s84, 0xc2000
	buffer_load_dwordx4 v[8:11], v225, s[68:71], s85 offen
	s_waitcnt vmcnt(7)
	v_mfma_f32_16x16x32_bf16 v[68:71], v[12:15], v[164:167], v[68:71]
	v_mfma_f32_16x16x32_bf16 v[124:127], v[12:15], v[172:175], v[124:127]
	s_add_u32 s85, s84, 0xc2000
	buffer_load_dwordx4 v[12:15], v225, s[68:71], s85 offen offset:64
	s_waitcnt vmcnt(7)
	v_mfma_f32_16x16x32_bf16 v[72:75], v[16:19], v[160:163], v[72:75]
	v_mfma_f32_16x16x32_bf16 v[128:131], v[16:19], v[168:171], v[128:131]
	s_add_u32 s85, s84, 0xe0000
	buffer_load_dwordx4 v[16:19], v225, s[68:71], s85 offen
	s_waitcnt vmcnt(7)
	v_mfma_f32_16x16x32_bf16 v[72:75], v[20:23], v[164:167], v[72:75]
	v_mfma_f32_16x16x32_bf16 v[128:131], v[20:23], v[172:175], v[128:131]
	s_add_u32 s85, s84, 0xe0000
	buffer_load_dwordx4 v[20:23], v225, s[68:71], s85 offen offset:64
	s_waitcnt vmcnt(7)
	v_mfma_f32_16x16x32_bf16 v[76:79], v[24:27], v[160:163], v[76:79]
	v_mfma_f32_16x16x32_bf16 v[132:135], v[24:27], v[168:171], v[132:135]
	s_add_u32 s85, s84, 0xe2000
	buffer_load_dwordx4 v[24:27], v225, s[68:71], s85 offen
	s_waitcnt vmcnt(7)
	v_mfma_f32_16x16x32_bf16 v[76:79], v[28:31], v[164:167], v[76:79]
	v_mfma_f32_16x16x32_bf16 v[132:135], v[28:31], v[172:175], v[132:135]
	s_add_u32 s85, s84, 0xe2000
	buffer_load_dwordx4 v[28:31], v225, s[68:71], s85 offen offset:64
	s_waitcnt vmcnt(7)
	v_mfma_f32_16x16x32_bf16 v[80:83], v[0:3], v[160:163], v[80:83]
	v_mfma_f32_16x16x32_bf16 v[136:139], v[0:3], v[168:171], v[136:139]
	s_add_u32 s85, s84, 0x100000
	buffer_load_dwordx4 v[0:3], v225, s[68:71], s85 offen
	s_waitcnt vmcnt(7)
	v_mfma_f32_16x16x32_bf16 v[80:83], v[4:7], v[164:167], v[80:83]
	v_mfma_f32_16x16x32_bf16 v[136:139], v[4:7], v[172:175], v[136:139]
	s_add_u32 s85, s84, 0x100000
	buffer_load_dwordx4 v[4:7], v225, s[68:71], s85 offen offset:64
	s_waitcnt vmcnt(7)
	v_mfma_f32_16x16x32_bf16 v[84:87], v[8:11], v[160:163], v[84:87]
	v_mfma_f32_16x16x32_bf16 v[140:143], v[8:11], v[168:171], v[140:143]
	s_add_u32 s85, s84, 0x102000
	buffer_load_dwordx4 v[8:11], v225, s[68:71], s85 offen
	s_waitcnt vmcnt(7)
	v_mfma_f32_16x16x32_bf16 v[84:87], v[12:15], v[164:167], v[84:87]
	v_mfma_f32_16x16x32_bf16 v[140:143], v[12:15], v[172:175], v[140:143]
	s_add_u32 s85, s84, 0x102000
	buffer_load_dwordx4 v[12:15], v225, s[68:71], s85 offen offset:64
	s_waitcnt vmcnt(7)
; __device__ __forceinline__ void nat_phase(const Params& p, float* ldsf, int wave0, int nwaves) {
;     ...
;             float mx = -1e30f;
; #pragma unroll
;             for (int i = 0; i < 8; ++i)
; #pragma unroll
;                 for (int hf = 0; hf < 2; ++hf)
; #pragma unroll
;                     for (int j = 0; j < 4; ++j) { const int kc = cs0 + lq * 8 + hf * 4 + j; const bool valid = (kc >= csq) && (kc < csq + 16); const int bc = valid ? (kc - c + 15) : 0;
;                         const float s = valid ? sc[i][hf][j] * 0.125f + tb[i * 31 + bc] : -1e30f; sc[i][hf][j] = s; mx = fmaxf(mx, s); }
;             mx = fmaxf(mx, __shfl_xor(mx, 16)); mx = fmaxf(mx, __shfl_xor(mx, 32));
;             float sum = 0.f;
; #pragma unroll
;             for (int i = 0; i < 8; ++i)
; #pragma unroll
;                 for (int hf = 0; hf < 2; ++hf)
; #pragma unroll
;                     for (int j = 0; j < 4; ++j) { const float e = __expf(sc[i][hf][j] - mx); sc[i][hf][j] = e; sum += e; }
	v_mfma_f32_16x16x32_bf16 v[88:91], v[16:19], v[160:163], v[88:91]
	v_mfma_f32_16x16x32_bf16 v[144:147], v[16:19], v[168:171], v[144:147]
	s_waitcnt vmcnt(6)
	v_mfma_f32_16x16x32_bf16 v[88:91], v[20:23], v[164:167], v[88:91]
	v_mfma_f32_16x16x32_bf16 v[144:147], v[20:23], v[172:175], v[144:147]
	s_waitcnt vmcnt(5)
	v_mfma_f32_16x16x32_bf16 v[92:95], v[24:27], v[160:163], v[92:95]
	v_mfma_f32_16x16x32_bf16 v[148:151], v[24:27], v[168:171], v[148:151]
	s_waitcnt vmcnt(4)
	v_mfma_f32_16x16x32_bf16 v[92:95], v[28:31], v[164:167], v[92:95]
	v_mfma_f32_16x16x32_bf16 v[148:151], v[28:31], v[172:175], v[148:151]
	s_waitcnt vmcnt(3)
	v_mfma_f32_16x16x32_bf16 v[152:155], v[0:3], v[168:171], v[152:155]
	s_waitcnt vmcnt(2)
	v_mfma_f32_16x16x32_bf16 v[152:155], v[4:7], v[172:175], v[152:155]
	s_waitcnt vmcnt(1)
	v_mfma_f32_16x16x32_bf16 v[156:159], v[8:11], v[168:171], v[156:159]
	s_waitcnt vmcnt(0)
	v_mfma_f32_16x16x32_bf16 v[156:159], v[12:15], v[172:175], v[156:159]
	s_lshl_b32 s84, s82, 11
	s_add_u32 s84, s84, s79
	buffer_load_dwordx2 v[208:209], v227, s[68:71], s84 offen offset:0
	buffer_load_dwordx2 v[210:211], v227, s[68:71], s84 offen offset:32
	buffer_load_dwordx2 v[212:213], v227, s[68:71], s84 offen offset:64
	buffer_load_dwordx2 v[214:215], v227, s[68:71], s84 offen offset:96
	s_add_u32 s85, s84, 0x20000
	buffer_load_dwordx2 v[216:217], v227, s[68:71], s85 offen offset:0
	buffer_load_dwordx2 v[218:219], v227, s[68:71], s85 offen offset:32
	buffer_load_dwordx2 v[220:221], v227, s[68:71], s85 offen offset:64
	buffer_load_dwordx2 v[222:223], v227, s[68:71], s85 offen offset:96
	s_lshl_b32 s84, s83, 1
	s_add_u32 s84, s84, s78
	s_add_u32 s85, s84, 0x80000
	s_add_u32 s86, s84, 0x100000
	s_add_u32 s87, s84, 0x180000
	buffer_load_dwordx4 v[0:3], v226, s[68:71], s84 offen offset:0
	buffer_load_dwordx4 v[4:7], v226, s[68:71], s85 offen offset:0
	buffer_load_dwordx4 v[8:11], v226, s[68:71], s86 offen offset:0
	buffer_load_dwordx4 v[12:15], v226, s[68:71], s87 offen offset:0
	buffer_load_dwordx4 v[16:19], v226, s[68:71], s84 offen offset:128
	buffer_load_dwordx4 v[20:23], v226, s[68:71], s85 offen offset:128
	buffer_load_dwordx4 v[24:27], v226, s[68:71], s86 offen offset:128
	buffer_load_dwordx4 v[28:31], v226, s[68:71], s87 offen offset:128
	v_max3_f32 v239, v32, v33, v34
	v_max3_f32 v239, v239, v35, v36
	v_max3_f32 v239, v239, v37, v38
	v_max3_f32 v239, v239, v39, v40
	v_max3_f32 v239, v239, v41, v42
	v_max3_f32 v239, v239, v43, v44
	v_max3_f32 v239, v239, v45, v46
	v_max3_f32 v239, v239, v47, v48
	v_max3_f32 v239, v239, v49, v50
	v_max3_f32 v239, v239, v51, v52
	v_max3_f32 v239, v239, v53, v54
	v_max3_f32 v239, v239, v55, v56
	v_max3_f32 v239, v239, v57, v58
	v_max3_f32 v239, v239, v59, v60
	v_max3_f32 v239, v239, v61, v62
	v_max3_f32 v239, v239, v63, v64
	v_max3_f32 v239, v239, v65, v66
	v_max3_f32 v239, v239, v67, v68
	v_max3_f32 v239, v239, v69, v70
	v_max3_f32 v239, v239, v71, v72
	v_max3_f32 v239, v239, v73, v74
	v_max3_f32 v239, v239, v75, v76
	v_max3_f32 v239, v239, v77, v78
	v_max3_f32 v239, v239, v79, v80
	v_max3_f32 v239, v239, v81, v82
	v_max3_f32 v239, v239, v83, v84
	v_max3_f32 v239, v239, v85, v86
	v_max3_f32 v239, v239, v87, v88
	v_max3_f32 v239, v239, v89, v90
	v_max3_f32 v239, v239, v91, v92
	v_max3_f32 v239, v239, v93, v94
	v_max_f32_e32 v239, v239, v95
	ds_bpermute_b32 v242, v248, v239
	s_waitcnt lgkmcnt(0)
	v_max_f32_e32 v239, v239, v242
	ds_bpermute_b32 v242, v249, v239
	s_waitcnt lgkmcnt(0)
	v_max_f32_e32 v239, v239, v242
	v_mul_f32_e64 v242, -v239, v252
	v_mov_b32_e32 v243, v242
	v_pk_fma_f32 v[32:33], v[32:33], v[252:253], v[242:243]
	v_pk_fma_f32 v[34:35], v[34:35], v[252:253], v[242:243]
	v_pk_fma_f32 v[36:37], v[36:37], v[252:253], v[242:243]
	v_pk_fma_f32 v[38:39], v[38:39], v[252:253], v[242:243]
	v_pk_fma_f32 v[40:41], v[40:41], v[252:253], v[242:243]
	v_pk_fma_f32 v[42:43], v[42:43], v[252:253], v[242:243]
	v_pk_fma_f32 v[44:45], v[44:45], v[252:253], v[242:243]
	v_pk_fma_f32 v[46:47], v[46:47], v[252:253], v[242:243]
	v_pk_fma_f32 v[48:49], v[48:49], v[252:253], v[242:243]
	v_pk_fma_f32 v[50:51], v[50:51], v[252:253], v[242:243]
	v_pk_fma_f32 v[52:53], v[52:53], v[252:253], v[242:243]
	v_pk_fma_f32 v[54:55], v[54:55], v[252:253], v[242:243]
	v_pk_fma_f32 v[56:57], v[56:57], v[252:253], v[242:243]
	v_pk_fma_f32 v[58:59], v[58:59], v[252:253], v[242:243]
	v_pk_fma_f32 v[60:61], v[60:61], v[252:253], v[242:243]
	v_pk_fma_f32 v[62:63], v[62:63], v[252:253], v[242:243]
	v_pk_fma_f32 v[64:65], v[64:65], v[252:253], v[242:243]
	v_pk_fma_f32 v[66:67], v[66:67], v[252:253], v[242:243]
	v_pk_fma_f32 v[68:69], v[68:69], v[252:253], v[242:243]
	v_pk_fma_f32 v[70:71], v[70:71], v[252:253], v[242:243]
	v_pk_fma_f32 v[72:73], v[72:73], v[252:253], v[242:243]
	v_pk_fma_f32 v[74:75], v[74:75], v[252:253], v[242:243]
	v_pk_fma_f32 v[76:77], v[76:77], v[252:253], v[242:243]
	v_pk_fma_f32 v[78:79], v[78:79], v[252:253], v[242:243]
	v_pk_fma_f32 v[80:81], v[80:81], v[252:253], v[242:243]
	v_pk_fma_f32 v[82:83], v[82:83], v[252:253], v[242:243]
	v_pk_fma_f32 v[84:85], v[84:85], v[252:253], v[242:243]
	v_pk_fma_f32 v[86:87], v[86:87], v[252:253], v[242:243]
	v_pk_fma_f32 v[88:89], v[88:89], v[252:253], v[242:243]
	v_pk_fma_f32 v[90:91], v[90:91], v[252:253], v[242:243]
	v_pk_fma_f32 v[92:93], v[92:93], v[252:253], v[242:243]
	v_pk_fma_f32 v[94:95], v[94:95], v[252:253], v[242:243]
	v_exp_f32_e32 v32, v32
	v_exp_f32_e32 v33, v33
	v_exp_f32_e32 v34, v34
	v_exp_f32_e32 v35, v35
	v_exp_f32_e32 v36, v36
	v_exp_f32_e32 v37, v37
	v_exp_f32_e32 v38, v38
	v_exp_f32_e32 v39, v39
	v_exp_f32_e32 v40, v40
	v_exp_f32_e32 v41, v41
	v_exp_f32_e32 v42, v42
; __device__ __forceinline__ unsigned cvt_pk_bf16(float lo, float hi) { unsigned r; asm volatile("v_cvt_pk_bf16_f32 %0, %1, %2" : "=v"(r) : "v"(lo), "v"(hi)); return r; }
; __device__ __forceinline__ void nat_phase(const Params& p, float* ldsf, int wave0, int nwaves) {
;     ...
;             float sum = 0.f;
; #pragma unroll
;             for (int i = 0; i < 8; ++i)
; #pragma unroll
;                 for (int hf = 0; hf < 2; ++hf)
; #pragma unroll
;                     for (int j = 0; j < 4; ++j) { const float e = __expf(sc[i][hf][j] - mx); sc[i][hf][j] = e; sum += e; }
;             sum += __shfl_xor(sum, 16); sum += __shfl_xor(sum, 32);
;             const float inv = 1.0f / sum;
;             f32x4 o[4];
; #pragma unroll
;             for (int mt = 0; mt < 4; ++mt) o[mt] = (f32x4){0.f, 0.f, 0.f, 0.f};
; #pragma unroll
;             for (int i = 0; i < 8; ++i) {
;                 u32x4 pw; pw.x = cvt_pk_bf16(sc[i][0][0] * inv, sc[i][0][1] * inv); pw.y = cvt_pk_bf16(sc[i][0][2] * inv, sc[i][0][3] * inv);
;                 pw.z = cvt_pk_bf16(sc[i][1][0] * inv, sc[i][1][1] * inv); pw.w = cvt_pk_bf16(sc[i][1][2] * inv, sc[i][1][3] * inv);
	v_exp_f32_e32 v43, v43
	v_exp_f32_e32 v44, v44
	v_exp_f32_e32 v45, v45
	v_exp_f32_e32 v46, v46
	v_exp_f32_e32 v47, v47
	v_exp_f32_e32 v48, v48
	v_exp_f32_e32 v49, v49
	v_exp_f32_e32 v50, v50
	v_exp_f32_e32 v51, v51
	v_exp_f32_e32 v52, v52
	v_exp_f32_e32 v53, v53
	v_exp_f32_e32 v54, v54
	v_exp_f32_e32 v55, v55
	v_exp_f32_e32 v56, v56
	v_exp_f32_e32 v57, v57
	v_exp_f32_e32 v58, v58
	v_exp_f32_e32 v59, v59
	v_exp_f32_e32 v60, v60
	v_exp_f32_e32 v61, v61
	v_exp_f32_e32 v62, v62
	v_exp_f32_e32 v63, v63
	v_exp_f32_e32 v64, v64
	v_exp_f32_e32 v65, v65
	v_exp_f32_e32 v66, v66
	v_exp_f32_e32 v67, v67
	v_exp_f32_e32 v68, v68
	v_exp_f32_e32 v69, v69
	v_exp_f32_e32 v70, v70
	v_exp_f32_e32 v71, v71
	v_exp_f32_e32 v72, v72
	v_exp_f32_e32 v73, v73
	v_exp_f32_e32 v74, v74
	v_exp_f32_e32 v75, v75
	v_exp_f32_e32 v76, v76
	v_exp_f32_e32 v77, v77
	v_exp_f32_e32 v78, v78
	v_exp_f32_e32 v79, v79
	v_exp_f32_e32 v80, v80
	v_exp_f32_e32 v81, v81
	v_exp_f32_e32 v82, v82
	v_exp_f32_e32 v83, v83
	v_exp_f32_e32 v84, v84
	v_exp_f32_e32 v85, v85
	v_exp_f32_e32 v86, v86
	v_exp_f32_e32 v87, v87
	v_exp_f32_e32 v88, v88
	v_exp_f32_e32 v89, v89
	v_exp_f32_e32 v90, v90
	v_exp_f32_e32 v91, v91
	v_exp_f32_e32 v92, v92
	v_exp_f32_e32 v93, v93
	v_exp_f32_e32 v94, v94
	v_exp_f32_e32 v95, v95
	s_nop 0
	v_pk_add_f32 v[244:245], v[32:33], v[34:35]
	v_pk_add_f32 v[246:247], v[36:37], v[38:39]
	v_pk_add_f32 v[244:245], v[244:245], v[40:41]
	v_pk_add_f32 v[246:247], v[246:247], v[42:43]
	v_pk_add_f32 v[244:245], v[244:245], v[44:45]
	v_pk_add_f32 v[246:247], v[246:247], v[46:47]
	v_pk_add_f32 v[244:245], v[244:245], v[48:49]
	v_pk_add_f32 v[246:247], v[246:247], v[50:51]
	v_pk_add_f32 v[244:245], v[244:245], v[52:53]
	v_pk_add_f32 v[246:247], v[246:247], v[54:55]
	v_pk_add_f32 v[244:245], v[244:245], v[56:57]
	v_pk_add_f32 v[246:247], v[246:247], v[58:59]
	v_pk_add_f32 v[244:245], v[244:245], v[60:61]
	v_pk_add_f32 v[246:247], v[246:247], v[62:63]
	v_pk_add_f32 v[244:245], v[244:245], v[64:65]
	v_pk_add_f32 v[246:247], v[246:247], v[66:67]
	v_pk_add_f32 v[244:245], v[244:245], v[68:69]
	v_pk_add_f32 v[246:247], v[246:247], v[70:71]
	v_pk_add_f32 v[244:245], v[244:245], v[72:73]
	v_pk_add_f32 v[246:247], v[246:247], v[74:75]
	v_pk_add_f32 v[244:245], v[244:245], v[76:77]
	v_pk_add_f32 v[246:247], v[246:247], v[78:79]
	v_pk_add_f32 v[244:245], v[244:245], v[80:81]
	v_pk_add_f32 v[246:247], v[246:247], v[82:83]
	v_pk_add_f32 v[244:245], v[244:245], v[84:85]
	v_pk_add_f32 v[246:247], v[246:247], v[86:87]
	v_pk_add_f32 v[244:245], v[244:245], v[88:89]
	v_pk_add_f32 v[246:247], v[246:247], v[90:91]
	v_pk_add_f32 v[244:245], v[244:245], v[92:93]
	v_pk_add_f32 v[246:247], v[246:247], v[94:95]
	v_pk_add_f32 v[244:245], v[244:245], v[246:247]
	v_add_f32_e32 v240, v244, v245
	ds_bpermute_b32 v242, v248, v240
	s_waitcnt lgkmcnt(0)
	v_add_f32_e32 v240, v240, v242
	ds_bpermute_b32 v242, v249, v240
	s_waitcnt lgkmcnt(0)
	v_add_f32_e32 v240, v240, v242
	v_rcp_f32_e32 v242, v240
	s_nop 0
	v_mov_b32_e32 v243, v242
	v_pk_mul_f32 v[32:33], v[32:33], v[242:243]
	v_pk_mul_f32 v[34:35], v[34:35], v[242:243]
	v_pk_mul_f32 v[36:37], v[36:37], v[242:243]
	v_pk_mul_f32 v[38:39], v[38:39], v[242:243]
	v_pk_mul_f32 v[40:41], v[40:41], v[242:243]
	v_pk_mul_f32 v[42:43], v[42:43], v[242:243]
	v_pk_mul_f32 v[44:45], v[44:45], v[242:243]
	v_pk_mul_f32 v[46:47], v[46:47], v[242:243]
	v_pk_mul_f32 v[48:49], v[48:49], v[242:243]
	v_pk_mul_f32 v[50:51], v[50:51], v[242:243]
	v_pk_mul_f32 v[52:53], v[52:53], v[242:243]
	v_pk_mul_f32 v[54:55], v[54:55], v[242:243]
	v_pk_mul_f32 v[56:57], v[56:57], v[242:243]
	v_pk_mul_f32 v[58:59], v[58:59], v[242:243]
	v_pk_mul_f32 v[60:61], v[60:61], v[242:243]
	v_pk_mul_f32 v[62:63], v[62:63], v[242:243]
	v_pk_mul_f32 v[64:65], v[64:65], v[242:243]
	v_pk_mul_f32 v[66:67], v[66:67], v[242:243]
	v_pk_mul_f32 v[68:69], v[68:69], v[242:243]
	v_pk_mul_f32 v[70:71], v[70:71], v[242:243]
	v_pk_mul_f32 v[72:73], v[72:73], v[242:243]
	v_pk_mul_f32 v[74:75], v[74:75], v[242:243]
	v_pk_mul_f32 v[76:77], v[76:77], v[242:243]
	v_pk_mul_f32 v[78:79], v[78:79], v[242:243]
	v_pk_mul_f32 v[80:81], v[80:81], v[242:243]
	v_pk_mul_f32 v[82:83], v[82:83], v[242:243]
	v_pk_mul_f32 v[84:85], v[84:85], v[242:243]
	v_pk_mul_f32 v[86:87], v[86:87], v[242:243]
	v_pk_mul_f32 v[88:89], v[88:89], v[242:243]
	v_pk_mul_f32 v[90:91], v[90:91], v[242:243]
	v_pk_mul_f32 v[92:93], v[92:93], v[242:243]
	v_pk_mul_f32 v[94:95], v[94:95], v[242:243]
	v_cvt_pk_bf16_f32 v32, v32, v33
	v_cvt_pk_bf16_f32 v33, v34, v35
	v_cvt_pk_bf16_f32 v34, v36, v37
	v_cvt_pk_bf16_f32 v35, v38, v39
	v_cvt_pk_bf16_f32 v40, v40, v41
	v_cvt_pk_bf16_f32 v41, v42, v43
	v_cvt_pk_bf16_f32 v42, v44, v45
	v_cvt_pk_bf16_f32 v43, v46, v47
	v_cvt_pk_bf16_f32 v48, v48, v49
	v_cvt_pk_bf16_f32 v49, v50, v51
	v_cvt_pk_bf16_f32 v50, v52, v53
	v_cvt_pk_bf16_f32 v51, v54, v55
	v_cvt_pk_bf16_f32 v56, v56, v57
	v_cvt_pk_bf16_f32 v57, v58, v59
	v_cvt_pk_bf16_f32 v58, v60, v61
	v_cvt_pk_bf16_f32 v59, v62, v63
	v_cvt_pk_bf16_f32 v64, v64, v65
	v_cvt_pk_bf16_f32 v65, v66, v67
	v_cvt_pk_bf16_f32 v66, v68, v69
	v_cvt_pk_bf16_f32 v67, v70, v71
	v_cvt_pk_bf16_f32 v72, v72, v73
	v_cvt_pk_bf16_f32 v73, v74, v75
	v_cvt_pk_bf16_f32 v74, v76, v77
	v_cvt_pk_bf16_f32 v75, v78, v79
	v_cvt_pk_bf16_f32 v80, v80, v81
	v_cvt_pk_bf16_f32 v81, v82, v83
	v_cvt_pk_bf16_f32 v82, v84, v85
	v_cvt_pk_bf16_f32 v83, v86, v87
	v_cvt_pk_bf16_f32 v88, v88, v89
	v_cvt_pk_bf16_f32 v89, v90, v91
	v_cvt_pk_bf16_f32 v90, v92, v93
	v_cvt_pk_bf16_f32 v91, v94, v95
	v_max3_f32 v239, v96, v97, v98
	v_max3_f32 v239, v239, v99, v100
	v_max3_f32 v239, v239, v101, v102
	v_max3_f32 v239, v239, v103, v104
	v_max3_f32 v239, v239, v105, v106
	v_max3_f32 v239, v239, v107, v108
	v_max3_f32 v239, v239, v109, v110
	v_max3_f32 v239, v239, v111, v112
	v_max3_f32 v239, v239, v113, v114
	v_max3_f32 v239, v239, v115, v116
	v_max3_f32 v239, v239, v117, v118
	v_max3_f32 v239, v239, v119, v120
	v_max3_f32 v239, v239, v121, v122
	v_max3_f32 v239, v239, v123, v124
	v_max3_f32 v239, v239, v125, v126
	v_max3_f32 v239, v239, v127, v128
	v_max3_f32 v239, v239, v129, v130
	v_max3_f32 v239, v239, v131, v132
	v_max3_f32 v239, v239, v133, v134
	v_max3_f32 v239, v239, v135, v136
	v_max3_f32 v239, v239, v137, v138
	v_max3_f32 v239, v239, v139, v140
	v_max3_f32 v239, v239, v141, v142
	v_max3_f32 v239, v239, v143, v144
	v_max3_f32 v239, v239, v145, v146
	v_max3_f32 v239, v239, v147, v148
	v_max3_f32 v239, v239, v149, v150
	v_max3_f32 v239, v239, v151, v152
	v_max3_f32 v239, v239, v153, v154
	v_max3_f32 v239, v239, v155, v156
	v_max3_f32 v239, v239, v157, v158
	v_max_f32_e32 v239, v239, v159
	ds_bpermute_b32 v242, v248, v239
	s_waitcnt lgkmcnt(0)
; __device__ __forceinline__ void nat_phase(const Params& p, float* ldsf, int wave0, int nwaves) {
;     ...
;             float mx = -1e30f;
; #pragma unroll
;             for (int i = 0; i < 8; ++i)
; #pragma unroll
;                 for (int hf = 0; hf < 2; ++hf)
; #pragma unroll
;                     for (int j = 0; j < 4; ++j) { const int kc = cs0 + lq * 8 + hf * 4 + j; const bool valid = (kc >= csq) && (kc < csq + 16); const int bc = valid ? (kc - c + 15) : 0;
;                         const float s = valid ? sc[i][hf][j] * 0.125f + tb[i * 31 + bc] : -1e30f; sc[i][hf][j] = s; mx = fmaxf(mx, s); }
;             mx = fmaxf(mx, __shfl_xor(mx, 16)); mx = fmaxf(mx, __shfl_xor(mx, 32));
;             float sum = 0.f;
; #pragma unroll
;             for (int i = 0; i < 8; ++i)
; #pragma unroll
;                 for (int hf = 0; hf < 2; ++hf)
; #pragma unroll
;                     for (int j = 0; j < 4; ++j) { const float e = __expf(sc[i][hf][j] - mx); sc[i][hf][j] = e; sum += e; }
;             sum += __shfl_xor(sum, 16); sum += __shfl_xor(sum, 32);
;             const float inv = 1.0f / sum;
	v_max_f32_e32 v239, v239, v242
	ds_bpermute_b32 v242, v249, v239
	s_waitcnt lgkmcnt(0)
	v_max_f32_e32 v239, v239, v242
	v_mul_f32_e64 v242, -v239, v252
	v_mov_b32_e32 v243, v242
	v_pk_fma_f32 v[96:97], v[96:97], v[252:253], v[242:243]
	v_pk_fma_f32 v[98:99], v[98:99], v[252:253], v[242:243]
	v_pk_fma_f32 v[100:101], v[100:101], v[252:253], v[242:243]
	v_pk_fma_f32 v[102:103], v[102:103], v[252:253], v[242:243]
	v_pk_fma_f32 v[104:105], v[104:105], v[252:253], v[242:243]
	v_pk_fma_f32 v[106:107], v[106:107], v[252:253], v[242:243]
	v_pk_fma_f32 v[108:109], v[108:109], v[252:253], v[242:243]
	v_pk_fma_f32 v[110:111], v[110:111], v[252:253], v[242:243]
	v_pk_fma_f32 v[112:113], v[112:113], v[252:253], v[242:243]
	v_pk_fma_f32 v[114:115], v[114:115], v[252:253], v[242:243]
	v_pk_fma_f32 v[116:117], v[116:117], v[252:253], v[242:243]
	v_pk_fma_f32 v[118:119], v[118:119], v[252:253], v[242:243]
	v_pk_fma_f32 v[120:121], v[120:121], v[252:253], v[242:243]
	v_pk_fma_f32 v[122:123], v[122:123], v[252:253], v[242:243]
	v_pk_fma_f32 v[124:125], v[124:125], v[252:253], v[242:243]
	v_pk_fma_f32 v[126:127], v[126:127], v[252:253], v[242:243]
	v_pk_fma_f32 v[128:129], v[128:129], v[252:253], v[242:243]
	v_pk_fma_f32 v[130:131], v[130:131], v[252:253], v[242:243]
	v_pk_fma_f32 v[132:133], v[132:133], v[252:253], v[242:243]
	v_pk_fma_f32 v[134:135], v[134:135], v[252:253], v[242:243]
	v_pk_fma_f32 v[136:137], v[136:137], v[252:253], v[242:243]
	v_pk_fma_f32 v[138:139], v[138:139], v[252:253], v[242:243]
	v_pk_fma_f32 v[140:141], v[140:141], v[252:253], v[242:243]
	v_pk_fma_f32 v[142:143], v[142:143], v[252:253], v[242:243]
	v_pk_fma_f32 v[144:145], v[144:145], v[252:253], v[242:243]
	v_pk_fma_f32 v[146:147], v[146:147], v[252:253], v[242:243]
	v_pk_fma_f32 v[148:149], v[148:149], v[252:253], v[242:243]
	v_pk_fma_f32 v[150:151], v[150:151], v[252:253], v[242:243]
	v_pk_fma_f32 v[152:153], v[152:153], v[252:253], v[242:243]
	v_pk_fma_f32 v[154:155], v[154:155], v[252:253], v[242:243]
	v_pk_fma_f32 v[156:157], v[156:157], v[252:253], v[242:243]
	v_pk_fma_f32 v[158:159], v[158:159], v[252:253], v[242:243]
	v_exp_f32_e32 v96, v96
	v_exp_f32_e32 v97, v97
	v_exp_f32_e32 v98, v98
	v_exp_f32_e32 v99, v99
	v_exp_f32_e32 v100, v100
	v_exp_f32_e32 v101, v101
	v_exp_f32_e32 v102, v102
	v_exp_f32_e32 v103, v103
	v_exp_f32_e32 v104, v104
	v_exp_f32_e32 v105, v105
	v_exp_f32_e32 v106, v106
	v_exp_f32_e32 v107, v107
	v_exp_f32_e32 v108, v108
	v_exp_f32_e32 v109, v109
	v_exp_f32_e32 v110, v110
	v_exp_f32_e32 v111, v111
	v_exp_f32_e32 v112, v112
	v_exp_f32_e32 v113, v113
	v_exp_f32_e32 v114, v114
	v_exp_f32_e32 v115, v115
	v_exp_f32_e32 v116, v116
	v_exp_f32_e32 v117, v117
	v_exp_f32_e32 v118, v118
	v_exp_f32_e32 v119, v119
	v_exp_f32_e32 v120, v120
	v_exp_f32_e32 v121, v121
	v_exp_f32_e32 v122, v122
	v_exp_f32_e32 v123, v123
	v_exp_f32_e32 v124, v124
	v_exp_f32_e32 v125, v125
	v_exp_f32_e32 v126, v126
	v_exp_f32_e32 v127, v127
	v_exp_f32_e32 v128, v128
	v_exp_f32_e32 v129, v129
	v_exp_f32_e32 v130, v130
	v_exp_f32_e32 v131, v131
	v_exp_f32_e32 v132, v132
	v_exp_f32_e32 v133, v133
	v_exp_f32_e32 v134, v134
	v_exp_f32_e32 v135, v135
	v_exp_f32_e32 v136, v136
	v_exp_f32_e32 v137, v137
	v_exp_f32_e32 v138, v138
	v_exp_f32_e32 v139, v139
	v_exp_f32_e32 v140, v140
	v_exp_f32_e32 v141, v141
	v_exp_f32_e32 v142, v142
	v_exp_f32_e32 v143, v143
	v_exp_f32_e32 v144, v144
	v_exp_f32_e32 v145, v145
	v_exp_f32_e32 v146, v146
	v_exp_f32_e32 v147, v147
	v_exp_f32_e32 v148, v148
	v_exp_f32_e32 v149, v149
	v_exp_f32_e32 v150, v150
	v_exp_f32_e32 v151, v151
	v_exp_f32_e32 v152, v152
	v_exp_f32_e32 v153, v153
	v_exp_f32_e32 v154, v154
	v_exp_f32_e32 v155, v155
	v_exp_f32_e32 v156, v156
	v_exp_f32_e32 v157, v157
	v_exp_f32_e32 v158, v158
	v_exp_f32_e32 v159, v159
	s_nop 0
	v_pk_add_f32 v[244:245], v[96:97], v[98:99]
	v_pk_add_f32 v[246:247], v[100:101], v[102:103]
	v_pk_add_f32 v[244:245], v[244:245], v[104:105]
	v_pk_add_f32 v[246:247], v[246:247], v[106:107]
	v_pk_add_f32 v[244:245], v[244:245], v[108:109]
	v_pk_add_f32 v[246:247], v[246:247], v[110:111]
	v_pk_add_f32 v[244:245], v[244:245], v[112:113]
	v_pk_add_f32 v[246:247], v[246:247], v[114:115]
	v_pk_add_f32 v[244:245], v[244:245], v[116:117]
	v_pk_add_f32 v[246:247], v[246:247], v[118:119]
	v_pk_add_f32 v[244:245], v[244:245], v[120:121]
	v_pk_add_f32 v[246:247], v[246:247], v[122:123]
	v_pk_add_f32 v[244:245], v[244:245], v[124:125]
	v_pk_add_f32 v[246:247], v[246:247], v[126:127]
	v_pk_add_f32 v[244:245], v[244:245], v[128:129]
	v_pk_add_f32 v[246:247], v[246:247], v[130:131]
	v_pk_add_f32 v[244:245], v[244:245], v[132:133]
	v_pk_add_f32 v[246:247], v[246:247], v[134:135]
	v_pk_add_f32 v[244:245], v[244:245], v[136:137]
	v_pk_add_f32 v[246:247], v[246:247], v[138:139]
	v_pk_add_f32 v[244:245], v[244:245], v[140:141]
	v_pk_add_f32 v[246:247], v[246:247], v[142:143]
	v_pk_add_f32 v[244:245], v[244:245], v[144:145]
	v_pk_add_f32 v[246:247], v[246:247], v[146:147]
	v_pk_add_f32 v[244:245], v[244:245], v[148:149]
	v_pk_add_f32 v[246:247], v[246:247], v[150:151]
	v_pk_add_f32 v[244:245], v[244:245], v[152:153]
	v_pk_add_f32 v[246:247], v[246:247], v[154:155]
	v_pk_add_f32 v[244:245], v[244:245], v[156:157]
	v_pk_add_f32 v[246:247], v[246:247], v[158:159]
	v_pk_add_f32 v[244:245], v[244:245], v[246:247]
	v_add_f32_e32 v240, v244, v245
	ds_bpermute_b32 v242, v248, v240
	s_waitcnt lgkmcnt(0)
	v_add_f32_e32 v240, v240, v242
	ds_bpermute_b32 v242, v249, v240
	s_waitcnt lgkmcnt(0)
; __device__ __forceinline__ unsigned cvt_pk_bf16(float lo, float hi) { unsigned r; asm volatile("v_cvt_pk_bf16_f32 %0, %1, %2" : "=v"(r) : "v"(lo), "v"(hi)); return r; }
; __device__ __forceinline__ void nat_phase(const Params& p, float* ldsf, int wave0, int nwaves) {
;     ...
;             const float inv = 1.0f / sum;
;             f32x4 o[4];
; #pragma unroll
;             for (int mt = 0; mt < 4; ++mt) o[mt] = (f32x4){0.f, 0.f, 0.f, 0.f};
; #pragma unroll
;             for (int i = 0; i < 8; ++i) {
;                 u32x4 pw; pw.x = cvt_pk_bf16(sc[i][0][0] * inv, sc[i][0][1] * inv); pw.y = cvt_pk_bf16(sc[i][0][2] * inv, sc[i][0][3] * inv);
;                 pw.z = cvt_pk_bf16(sc[i][1][0] * inv, sc[i][1][1] * inv); pw.w = cvt_pk_bf16(sc[i][1][2] * inv, sc[i][1][3] * inv);
;                 const bf16x8 bp = __builtin_bit_cast(bf16x8, pw);
; #pragma unroll
;                 for (int mt = 0; mt < 4; ++mt) { const u16* vp = Vb + (size_t)(mt * 16 + l15) * SEQ + i * 64 + cs0 + lq * 8;
;                     o[mt] = __builtin_amdgcn_mfma_f32_16x16x32_bf16(*(const bf16x8*)vp, bp, o[mt], 0, 0, 0); }
;             }
	v_add_f32_e32 v240, v240, v242
	v_rcp_f32_e32 v242, v240
	s_nop 0
	v_mov_b32_e32 v243, v242
	v_pk_mul_f32 v[96:97], v[96:97], v[242:243]
	v_pk_mul_f32 v[98:99], v[98:99], v[242:243]
	v_pk_mul_f32 v[100:101], v[100:101], v[242:243]
	v_pk_mul_f32 v[102:103], v[102:103], v[242:243]
	v_pk_mul_f32 v[104:105], v[104:105], v[242:243]
	v_pk_mul_f32 v[106:107], v[106:107], v[242:243]
	v_pk_mul_f32 v[108:109], v[108:109], v[242:243]
	v_pk_mul_f32 v[110:111], v[110:111], v[242:243]
	v_pk_mul_f32 v[112:113], v[112:113], v[242:243]
	v_pk_mul_f32 v[114:115], v[114:115], v[242:243]
	v_pk_mul_f32 v[116:117], v[116:117], v[242:243]
	v_pk_mul_f32 v[118:119], v[118:119], v[242:243]
	v_pk_mul_f32 v[120:121], v[120:121], v[242:243]
	v_pk_mul_f32 v[122:123], v[122:123], v[242:243]
	v_pk_mul_f32 v[124:125], v[124:125], v[242:243]
	v_pk_mul_f32 v[126:127], v[126:127], v[242:243]
	v_pk_mul_f32 v[128:129], v[128:129], v[242:243]
	v_pk_mul_f32 v[130:131], v[130:131], v[242:243]
	v_pk_mul_f32 v[132:133], v[132:133], v[242:243]
	v_pk_mul_f32 v[134:135], v[134:135], v[242:243]
	v_pk_mul_f32 v[136:137], v[136:137], v[242:243]
	v_pk_mul_f32 v[138:139], v[138:139], v[242:243]
	v_pk_mul_f32 v[140:141], v[140:141], v[242:243]
	v_pk_mul_f32 v[142:143], v[142:143], v[242:243]
	v_pk_mul_f32 v[144:145], v[144:145], v[242:243]
	v_pk_mul_f32 v[146:147], v[146:147], v[242:243]
	v_pk_mul_f32 v[148:149], v[148:149], v[242:243]
	v_pk_mul_f32 v[150:151], v[150:151], v[242:243]
	v_pk_mul_f32 v[152:153], v[152:153], v[242:243]
	v_pk_mul_f32 v[154:155], v[154:155], v[242:243]
	v_pk_mul_f32 v[156:157], v[156:157], v[242:243]
	v_pk_mul_f32 v[158:159], v[158:159], v[242:243]
	v_cvt_pk_bf16_f32 v96, v96, v97
	v_cvt_pk_bf16_f32 v97, v98, v99
	v_cvt_pk_bf16_f32 v98, v100, v101
	v_cvt_pk_bf16_f32 v99, v102, v103
	v_cvt_pk_bf16_f32 v104, v104, v105
	v_cvt_pk_bf16_f32 v105, v106, v107
	v_cvt_pk_bf16_f32 v106, v108, v109
	v_cvt_pk_bf16_f32 v107, v110, v111
	v_cvt_pk_bf16_f32 v112, v112, v113
	v_cvt_pk_bf16_f32 v113, v114, v115
	v_cvt_pk_bf16_f32 v114, v116, v117
	v_cvt_pk_bf16_f32 v115, v118, v119
	v_cvt_pk_bf16_f32 v120, v120, v121
	v_cvt_pk_bf16_f32 v121, v122, v123
	v_cvt_pk_bf16_f32 v122, v124, v125
	v_cvt_pk_bf16_f32 v123, v126, v127
	v_cvt_pk_bf16_f32 v128, v128, v129
	v_cvt_pk_bf16_f32 v129, v130, v131
	v_cvt_pk_bf16_f32 v130, v132, v133
	v_cvt_pk_bf16_f32 v131, v134, v135
	v_cvt_pk_bf16_f32 v136, v136, v137
	v_cvt_pk_bf16_f32 v137, v138, v139
	v_cvt_pk_bf16_f32 v138, v140, v141
	v_cvt_pk_bf16_f32 v139, v142, v143
	v_cvt_pk_bf16_f32 v144, v144, v145
	v_cvt_pk_bf16_f32 v145, v146, v147
	v_cvt_pk_bf16_f32 v146, v148, v149
	v_cvt_pk_bf16_f32 v147, v150, v151
	v_cvt_pk_bf16_f32 v152, v152, v153
	v_cvt_pk_bf16_f32 v153, v154, v155
	v_cvt_pk_bf16_f32 v154, v156, v157
	v_cvt_pk_bf16_f32 v155, v158, v159
	s_waitcnt vmcnt(7)
	v_mfma_f32_16x16x32_bf16 v[176:179], v[0:3], v[32:35], 0
	buffer_load_dwordx4 v[0:3], v226, s[68:71], s84 offen offset:256
	s_waitcnt vmcnt(7)
	v_mfma_f32_16x16x32_bf16 v[180:183], v[4:7], v[32:35], 0
	buffer_load_dwordx4 v[4:7], v226, s[68:71], s85 offen offset:256
	s_waitcnt vmcnt(7)
	v_mfma_f32_16x16x32_bf16 v[184:187], v[8:11], v[32:35], 0
	buffer_load_dwordx4 v[8:11], v226, s[68:71], s86 offen offset:256
	s_waitcnt vmcnt(7)
	v_mfma_f32_16x16x32_bf16 v[188:191], v[12:15], v[32:35], 0
	buffer_load_dwordx4 v[12:15], v226, s[68:71], s87 offen offset:256
	s_waitcnt vmcnt(7)
	v_mfma_f32_16x16x32_bf16 v[176:179], v[16:19], v[40:43], v[176:179]
	v_mfma_f32_16x16x32_bf16 v[192:195], v[16:19], v[96:99], 0
	buffer_load_dwordx4 v[16:19], v226, s[68:71], s84 offen offset:384
	s_waitcnt vmcnt(7)
	v_mfma_f32_16x16x32_bf16 v[180:183], v[20:23], v[40:43], v[180:183]
	v_mfma_f32_16x16x32_bf16 v[196:199], v[20:23], v[96:99], 0
	buffer_load_dwordx4 v[20:23], v226, s[68:71], s85 offen offset:384
	s_waitcnt vmcnt(7)
	v_mfma_f32_16x16x32_bf16 v[184:187], v[24:27], v[40:43], v[184:187]
	v_mfma_f32_16x16x32_bf16 v[200:203], v[24:27], v[96:99], 0
	buffer_load_dwordx4 v[24:27], v226, s[68:71], s86 offen offset:384
	s_waitcnt vmcnt(7)
	v_mfma_f32_16x16x32_bf16 v[188:191], v[28:31], v[40:43], v[188:191]
	v_mfma_f32_16x16x32_bf16 v[204:207], v[28:31], v[96:99], 0
	buffer_load_dwordx4 v[28:31], v226, s[68:71], s87 offen offset:384
	s_waitcnt vmcnt(7)
	v_mfma_f32_16x16x32_bf16 v[176:179], v[0:3], v[48:51], v[176:179]
	v_mfma_f32_16x16x32_bf16 v[192:195], v[0:3], v[104:107], v[192:195]
	buffer_load_dwordx4 v[0:3], v226, s[68:71], s84 offen offset:512
	s_waitcnt vmcnt(7)
	v_mfma_f32_16x16x32_bf16 v[180:183], v[4:7], v[48:51], v[180:183]
	v_mfma_f32_16x16x32_bf16 v[196:199], v[4:7], v[104:107], v[196:199]
	buffer_load_dwordx4 v[4:7], v226, s[68:71], s85 offen offset:512
	s_waitcnt vmcnt(7)
	v_mfma_f32_16x16x32_bf16 v[184:187], v[8:11], v[48:51], v[184:187]
	v_mfma_f32_16x16x32_bf16 v[200:203], v[8:11], v[104:107], v[200:203]
	buffer_load_dwordx4 v[8:11], v226, s[68:71], s86 offen offset:512
	s_waitcnt vmcnt(7)
	v_mfma_f32_16x16x32_bf16 v[188:191], v[12:15], v[48:51], v[188:191]
	v_mfma_f32_16x16x32_bf16 v[204:207], v[12:15], v[104:107], v[204:207]
	buffer_load_dwordx4 v[12:15], v226, s[68:71], s87 offen offset:512
	s_waitcnt vmcnt(7)
	v_mfma_f32_16x16x32_bf16 v[176:179], v[16:19], v[56:59], v[176:179]
	v_mfma_f32_16x16x32_bf16 v[192:195], v[16:19], v[112:115], v[192:195]
	buffer_load_dwordx4 v[16:19], v226, s[68:71], s84 offen offset:640
	s_waitcnt vmcnt(7)
	v_mfma_f32_16x16x32_bf16 v[180:183], v[20:23], v[56:59], v[180:183]
	v_mfma_f32_16x16x32_bf16 v[196:199], v[20:23], v[112:115], v[196:199]
	buffer_load_dwordx4 v[20:23], v226, s[68:71], s85 offen offset:640
	s_waitcnt vmcnt(7)
; __device__ __forceinline__ float bflo(unsigned w) { return __uint_as_float(w << 16); }
; __device__ __forceinline__ float bfhi(unsigned w) { return __uint_as_float(w & 0xffff0000u); }
; __device__ __forceinline__ unsigned cvt_pk_bf16(float lo, float hi) { unsigned r; asm volatile("v_cvt_pk_bf16_f32 %0, %1, %2" : "=v"(r) : "v"(lo), "v"(hi)); return r; }
; __device__ __forceinline__ float sigmoidf_(float x) { return __builtin_amdgcn_rcpf(1.0f + __expf(-x)); }
; __device__ __forceinline__ void nat_phase(const Params& p, float* ldsf, int wave0, int nwaves) {
;     ...
; #pragma unroll
;             for (int i = 0; i < 8; ++i) {
;                 u32x4 pw; pw.x = cvt_pk_bf16(sc[i][0][0] * inv, sc[i][0][1] * inv); pw.y = cvt_pk_bf16(sc[i][0][2] * inv, sc[i][0][3] * inv);
;                 pw.z = cvt_pk_bf16(sc[i][1][0] * inv, sc[i][1][1] * inv); pw.w = cvt_pk_bf16(sc[i][1][2] * inv, sc[i][1][3] * inv);
;                 const bf16x8 bp = __builtin_bit_cast(bf16x8, pw);
; #pragma unroll
;                 for (int mt = 0; mt < 4; ++mt) { const u16* vp = Vb + (size_t)(mt * 16 + l15) * SEQ + i * 64 + cs0 + lq * 8;
;                     o[mt] = __builtin_amdgcn_mfma_f32_16x16x32_bf16(*(const bf16x8*)vp, bp, o[mt], 0, 0, 0); }
;             }
;             const size_t tok = (size_t)(b * SEQ + r * 64 + c);
; #pragma unroll
;             for (int mt = 0; mt < 4; ++mt) { const int ch = h * 64 + mt * 16 + lq * 4; const u32x2 gw = *(const u32x2*)(Gn + tok * RW + ch);
;                 const float g0 = bflo(gw.x), g1 = bfhi(gw.x), g2 = bflo(gw.y), g3 = bfhi(gw.y);
;                 u32x2 w; w.x = cvt_pk_bf16(o[mt][0] * g0 * sigmoidf_(g0), o[mt][1] * g1 * sigmoidf_(g1)); w.y = cvt_pk_bf16(o[mt][2] * g2 * sigmoidf_(g2), o[mt][3] * g3 * sigmoidf_(g3));
	v_mfma_f32_16x16x32_bf16 v[184:187], v[24:27], v[56:59], v[184:187]
	v_mfma_f32_16x16x32_bf16 v[200:203], v[24:27], v[112:115], v[200:203]
	buffer_load_dwordx4 v[24:27], v226, s[68:71], s86 offen offset:640
	s_waitcnt vmcnt(7)
	v_mfma_f32_16x16x32_bf16 v[188:191], v[28:31], v[56:59], v[188:191]
	v_mfma_f32_16x16x32_bf16 v[204:207], v[28:31], v[112:115], v[204:207]
	buffer_load_dwordx4 v[28:31], v226, s[68:71], s87 offen offset:640
	s_waitcnt vmcnt(7)
	v_mfma_f32_16x16x32_bf16 v[176:179], v[0:3], v[64:67], v[176:179]
	v_mfma_f32_16x16x32_bf16 v[192:195], v[0:3], v[120:123], v[192:195]
	buffer_load_dwordx4 v[0:3], v226, s[68:71], s84 offen offset:768
	s_waitcnt vmcnt(7)
	v_mfma_f32_16x16x32_bf16 v[180:183], v[4:7], v[64:67], v[180:183]
	v_mfma_f32_16x16x32_bf16 v[196:199], v[4:7], v[120:123], v[196:199]
	buffer_load_dwordx4 v[4:7], v226, s[68:71], s85 offen offset:768
	s_waitcnt vmcnt(7)
	v_mfma_f32_16x16x32_bf16 v[184:187], v[8:11], v[64:67], v[184:187]
	v_mfma_f32_16x16x32_bf16 v[200:203], v[8:11], v[120:123], v[200:203]
	buffer_load_dwordx4 v[8:11], v226, s[68:71], s86 offen offset:768
	s_waitcnt vmcnt(7)
	v_mfma_f32_16x16x32_bf16 v[188:191], v[12:15], v[64:67], v[188:191]
	v_mfma_f32_16x16x32_bf16 v[204:207], v[12:15], v[120:123], v[204:207]
	buffer_load_dwordx4 v[12:15], v226, s[68:71], s87 offen offset:768
	s_waitcnt vmcnt(7)
	v_mfma_f32_16x16x32_bf16 v[176:179], v[16:19], v[72:75], v[176:179]
	v_mfma_f32_16x16x32_bf16 v[192:195], v[16:19], v[128:131], v[192:195]
	buffer_load_dwordx4 v[16:19], v226, s[68:71], s84 offen offset:896
	s_waitcnt vmcnt(7)
	v_mfma_f32_16x16x32_bf16 v[180:183], v[20:23], v[72:75], v[180:183]
	v_mfma_f32_16x16x32_bf16 v[196:199], v[20:23], v[128:131], v[196:199]
	buffer_load_dwordx4 v[20:23], v226, s[68:71], s85 offen offset:896
	s_waitcnt vmcnt(7)
	v_mfma_f32_16x16x32_bf16 v[184:187], v[24:27], v[72:75], v[184:187]
	v_mfma_f32_16x16x32_bf16 v[200:203], v[24:27], v[128:131], v[200:203]
	buffer_load_dwordx4 v[24:27], v226, s[68:71], s86 offen offset:896
	s_waitcnt vmcnt(7)
	v_mfma_f32_16x16x32_bf16 v[188:191], v[28:31], v[72:75], v[188:191]
	v_mfma_f32_16x16x32_bf16 v[204:207], v[28:31], v[128:131], v[204:207]
	buffer_load_dwordx4 v[28:31], v226, s[68:71], s87 offen offset:896
	s_waitcnt vmcnt(7)
	v_mfma_f32_16x16x32_bf16 v[176:179], v[0:3], v[80:83], v[176:179]
	v_mfma_f32_16x16x32_bf16 v[192:195], v[0:3], v[136:139], v[192:195]
	buffer_load_dwordx4 v[0:3], v226, s[68:71], s84 offen offset:1024
	s_waitcnt vmcnt(7)
	v_mfma_f32_16x16x32_bf16 v[180:183], v[4:7], v[80:83], v[180:183]
	v_mfma_f32_16x16x32_bf16 v[196:199], v[4:7], v[136:139], v[196:199]
	buffer_load_dwordx4 v[4:7], v226, s[68:71], s85 offen offset:1024
	s_waitcnt vmcnt(7)
	v_mfma_f32_16x16x32_bf16 v[184:187], v[8:11], v[80:83], v[184:187]
	v_mfma_f32_16x16x32_bf16 v[200:203], v[8:11], v[136:139], v[200:203]
	buffer_load_dwordx4 v[8:11], v226, s[68:71], s86 offen offset:1024
	s_waitcnt vmcnt(7)
	v_mfma_f32_16x16x32_bf16 v[188:191], v[12:15], v[80:83], v[188:191]
	v_mfma_f32_16x16x32_bf16 v[204:207], v[12:15], v[136:139], v[204:207]
	buffer_load_dwordx4 v[12:15], v226, s[68:71], s87 offen offset:1024
	s_waitcnt vmcnt(7)
	v_mfma_f32_16x16x32_bf16 v[176:179], v[16:19], v[88:91], v[176:179]
	v_mfma_f32_16x16x32_bf16 v[192:195], v[16:19], v[144:147], v[192:195]
	s_waitcnt vmcnt(6)
	v_mfma_f32_16x16x32_bf16 v[180:183], v[20:23], v[88:91], v[180:183]
	v_mfma_f32_16x16x32_bf16 v[196:199], v[20:23], v[144:147], v[196:199]
	s_waitcnt vmcnt(5)
	v_mfma_f32_16x16x32_bf16 v[184:187], v[24:27], v[88:91], v[184:187]
	v_mfma_f32_16x16x32_bf16 v[200:203], v[24:27], v[144:147], v[200:203]
	s_waitcnt vmcnt(4)
	v_mfma_f32_16x16x32_bf16 v[188:191], v[28:31], v[88:91], v[188:191]
	v_mfma_f32_16x16x32_bf16 v[204:207], v[28:31], v[144:147], v[204:207]
	s_waitcnt vmcnt(3)
	v_mfma_f32_16x16x32_bf16 v[192:195], v[0:3], v[152:155], v[192:195]
	s_waitcnt vmcnt(2)
	v_mfma_f32_16x16x32_bf16 v[196:199], v[4:7], v[152:155], v[196:199]
	s_waitcnt vmcnt(1)
	v_mfma_f32_16x16x32_bf16 v[200:203], v[8:11], v[152:155], v[200:203]
	s_waitcnt vmcnt(0)
	v_mfma_f32_16x16x32_bf16 v[204:207], v[12:15], v[152:155], v[204:207]
	s_waitcnt vmcnt(0)
	s_lshl_b32 s84, s82, 12
	s_add_u32 s84, s84, s80
	v_lshlrev_b32_e32 v36, 16, v208
	v_and_b32_e32 v37, 0xffff0000, v208
	v_lshlrev_b32_e32 v38, 16, v209
	v_and_b32_e32 v39, 0xffff0000, v209
	v_lshlrev_b32_e32 v44, 16, v210
	v_and_b32_e32 v45, 0xffff0000, v210
	v_lshlrev_b32_e32 v46, 16, v211
	v_and_b32_e32 v47, 0xffff0000, v211
	v_lshlrev_b32_e32 v52, 16, v212
	v_and_b32_e32 v53, 0xffff0000, v212
	v_lshlrev_b32_e32 v54, 16, v213
	v_and_b32_e32 v55, 0xffff0000, v213
	v_lshlrev_b32_e32 v60, 16, v214
	v_and_b32_e32 v61, 0xffff0000, v214
	v_lshlrev_b32_e32 v62, 16, v215
	v_and_b32_e32 v63, 0xffff0000, v215
	v_mul_f32_e32 v68, 0xbfb8aa3b, v36
	v_mul_f32_e32 v69, 0xbfb8aa3b, v37
	v_mul_f32_e32 v70, 0xbfb8aa3b, v38
	v_mul_f32_e32 v71, 0xbfb8aa3b, v39
	v_mul_f32_e32 v76, 0xbfb8aa3b, v44
	v_mul_f32_e32 v77, 0xbfb8aa3b, v45
	v_mul_f32_e32 v78, 0xbfb8aa3b, v46
	v_mul_f32_e32 v79, 0xbfb8aa3b, v47
	v_mul_f32_e32 v84, 0xbfb8aa3b, v52
	v_mul_f32_e32 v85, 0xbfb8aa3b, v53
	v_mul_f32_e32 v86, 0xbfb8aa3b, v54
	v_mul_f32_e32 v87, 0xbfb8aa3b, v55
	v_mul_f32_e32 v92, 0xbfb8aa3b, v60
	v_mul_f32_e32 v93, 0xbfb8aa3b, v61
	v_mul_f32_e32 v94, 0xbfb8aa3b, v62
	v_mul_f32_e32 v95, 0xbfb8aa3b, v63
	v_exp_f32_e32 v68, v68
	v_exp_f32_e32 v69, v69
	v_exp_f32_e32 v70, v70
	v_exp_f32_e32 v71, v71
	v_exp_f32_e32 v76, v76
	v_exp_f32_e32 v77, v77
	v_exp_f32_e32 v78, v78
	v_exp_f32_e32 v79, v79
	v_exp_f32_e32 v84, v84
	v_exp_f32_e32 v85, v85
	v_exp_f32_e32 v86, v86
	v_exp_f32_e32 v87, v87
; __device__ __forceinline__ float bflo(unsigned w) { return __uint_as_float(w << 16); }
; __device__ __forceinline__ float bfhi(unsigned w) { return __uint_as_float(w & 0xffff0000u); }
; __device__ __forceinline__ unsigned cvt_pk_bf16(float lo, float hi) { unsigned r; asm volatile("v_cvt_pk_bf16_f32 %0, %1, %2" : "=v"(r) : "v"(lo), "v"(hi)); return r; }
; __device__ __forceinline__ float sigmoidf_(float x) { return __builtin_amdgcn_rcpf(1.0f + __expf(-x)); }
; __device__ __forceinline__ void nat_phase(const Params& p, float* ldsf, int wave0, int nwaves) {
;     ...
;             const size_t tok = (size_t)(b * SEQ + r * 64 + c);
; #pragma unroll
;             for (int mt = 0; mt < 4; ++mt) { const int ch = h * 64 + mt * 16 + lq * 4; const u32x2 gw = *(const u32x2*)(Gn + tok * RW + ch);
;                 const float g0 = bflo(gw.x), g1 = bfhi(gw.x), g2 = bflo(gw.y), g3 = bfhi(gw.y);
;                 u32x2 w; w.x = cvt_pk_bf16(o[mt][0] * g0 * sigmoidf_(g0), o[mt][1] * g1 * sigmoidf_(g1)); w.y = cvt_pk_bf16(o[mt][2] * g2 * sigmoidf_(g2), o[mt][3] * g3 * sigmoidf_(g3));
;                 *(u32x2*)(MIX + tok * DM + 1024 + ch) = w; }
	v_exp_f32_e32 v92, v92
	v_exp_f32_e32 v93, v93
	v_exp_f32_e32 v94, v94
	v_exp_f32_e32 v95, v95
	s_nop 0
	v_add_f32_e32 v68, 1.0, v68
	v_add_f32_e32 v69, 1.0, v69
	v_add_f32_e32 v70, 1.0, v70
	v_add_f32_e32 v71, 1.0, v71
	v_add_f32_e32 v76, 1.0, v76
	v_add_f32_e32 v77, 1.0, v77
	v_add_f32_e32 v78, 1.0, v78
	v_add_f32_e32 v79, 1.0, v79
	v_add_f32_e32 v84, 1.0, v84
	v_add_f32_e32 v85, 1.0, v85
	v_add_f32_e32 v86, 1.0, v86
	v_add_f32_e32 v87, 1.0, v87
	v_add_f32_e32 v92, 1.0, v92
	v_add_f32_e32 v93, 1.0, v93
	v_add_f32_e32 v94, 1.0, v94
	v_add_f32_e32 v95, 1.0, v95
	v_rcp_f32_e32 v68, v68
	v_rcp_f32_e32 v69, v69
	v_rcp_f32_e32 v70, v70
	v_rcp_f32_e32 v71, v71
	v_rcp_f32_e32 v76, v76
	v_rcp_f32_e32 v77, v77
	v_rcp_f32_e32 v78, v78
	v_rcp_f32_e32 v79, v79
	v_rcp_f32_e32 v84, v84
	v_rcp_f32_e32 v85, v85
	v_rcp_f32_e32 v86, v86
	v_rcp_f32_e32 v87, v87
	v_rcp_f32_e32 v92, v92
	v_rcp_f32_e32 v93, v93
	v_rcp_f32_e32 v94, v94
	v_rcp_f32_e32 v95, v95
	s_nop 0
	v_mul_f32_e32 v176, v176, v36
	v_mul_f32_e32 v177, v177, v37
	v_mul_f32_e32 v178, v178, v38
	v_mul_f32_e32 v179, v179, v39
	v_mul_f32_e32 v180, v180, v44
	v_mul_f32_e32 v181, v181, v45
	v_mul_f32_e32 v182, v182, v46
	v_mul_f32_e32 v183, v183, v47
	v_mul_f32_e32 v184, v184, v52
	v_mul_f32_e32 v185, v185, v53
	v_mul_f32_e32 v186, v186, v54
	v_mul_f32_e32 v187, v187, v55
	v_mul_f32_e32 v188, v188, v60
	v_mul_f32_e32 v189, v189, v61
	v_mul_f32_e32 v190, v190, v62
	v_mul_f32_e32 v191, v191, v63
	v_mul_f32_e32 v176, v176, v68
	v_mul_f32_e32 v177, v177, v69
	v_mul_f32_e32 v178, v178, v70
	v_mul_f32_e32 v179, v179, v71
	v_mul_f32_e32 v180, v180, v76
	v_mul_f32_e32 v181, v181, v77
	v_mul_f32_e32 v182, v182, v78
	v_mul_f32_e32 v183, v183, v79
	v_mul_f32_e32 v184, v184, v84
	v_mul_f32_e32 v185, v185, v85
	v_mul_f32_e32 v186, v186, v86
	v_mul_f32_e32 v187, v187, v87
	v_mul_f32_e32 v188, v188, v92
	v_mul_f32_e32 v189, v189, v93
	v_mul_f32_e32 v190, v190, v94
	v_mul_f32_e32 v191, v191, v95
	v_cvt_pk_bf16_f32 v176, v176, v177
	v_cvt_pk_bf16_f32 v177, v178, v179
	v_cvt_pk_bf16_f32 v180, v180, v181
	v_cvt_pk_bf16_f32 v181, v182, v183
	v_cvt_pk_bf16_f32 v184, v184, v185
	v_cvt_pk_bf16_f32 v185, v186, v187
	v_cvt_pk_bf16_f32 v188, v188, v189
	v_cvt_pk_bf16_f32 v189, v190, v191
	buffer_store_dwordx2 v[176:177], v228, s[64:67], s84 offen offset:0
	buffer_store_dwordx2 v[180:181], v228, s[64:67], s84 offen offset:32
	buffer_store_dwordx2 v[184:185], v228, s[64:67], s84 offen offset:64
	buffer_store_dwordx2 v[188:189], v228, s[64:67], s84 offen offset:96
	s_add_u32 s85, s84, 0x40000
	v_lshlrev_b32_e32 v100, 16, v216
	v_and_b32_e32 v101, 0xffff0000, v216
	v_lshlrev_b32_e32 v102, 16, v217
	v_and_b32_e32 v103, 0xffff0000, v217
	v_lshlrev_b32_e32 v108, 16, v218
	v_and_b32_e32 v109, 0xffff0000, v218
	v_lshlrev_b32_e32 v110, 16, v219
	v_and_b32_e32 v111, 0xffff0000, v219
	v_lshlrev_b32_e32 v116, 16, v220
	v_and_b32_e32 v117, 0xffff0000, v220
	v_lshlrev_b32_e32 v118, 16, v221
	v_and_b32_e32 v119, 0xffff0000, v221
	v_lshlrev_b32_e32 v124, 16, v222
	v_and_b32_e32 v125, 0xffff0000, v222
	v_lshlrev_b32_e32 v126, 16, v223
	v_and_b32_e32 v127, 0xffff0000, v223
	v_mul_f32_e32 v132, 0xbfb8aa3b, v100
	v_mul_f32_e32 v133, 0xbfb8aa3b, v101
	v_mul_f32_e32 v134, 0xbfb8aa3b, v102
	v_mul_f32_e32 v135, 0xbfb8aa3b, v103
	v_mul_f32_e32 v140, 0xbfb8aa3b, v108
	v_mul_f32_e32 v141, 0xbfb8aa3b, v109
	v_mul_f32_e32 v142, 0xbfb8aa3b, v110
	v_mul_f32_e32 v143, 0xbfb8aa3b, v111
	v_mul_f32_e32 v148, 0xbfb8aa3b, v116
	v_mul_f32_e32 v149, 0xbfb8aa3b, v117
	v_mul_f32_e32 v150, 0xbfb8aa3b, v118
	v_mul_f32_e32 v151, 0xbfb8aa3b, v119
	v_mul_f32_e32 v156, 0xbfb8aa3b, v124
	v_mul_f32_e32 v157, 0xbfb8aa3b, v125
	v_mul_f32_e32 v158, 0xbfb8aa3b, v126
	v_mul_f32_e32 v159, 0xbfb8aa3b, v127
	v_exp_f32_e32 v132, v132
	v_exp_f32_e32 v133, v133
	v_exp_f32_e32 v134, v134
	v_exp_f32_e32 v135, v135
	v_exp_f32_e32 v140, v140
	v_exp_f32_e32 v141, v141
	v_exp_f32_e32 v142, v142
	v_exp_f32_e32 v143, v143
	v_exp_f32_e32 v148, v148
	v_exp_f32_e32 v149, v149
	v_exp_f32_e32 v150, v150
	v_exp_f32_e32 v151, v151
	v_exp_f32_e32 v156, v156
	v_exp_f32_e32 v157, v157
	v_exp_f32_e32 v158, v158
	v_exp_f32_e32 v159, v159
	s_nop 0
	v_add_f32_e32 v132, 1.0, v132
	v_add_f32_e32 v133, 1.0, v133
	v_add_f32_e32 v134, 1.0, v134
	v_add_f32_e32 v135, 1.0, v135
	v_add_f32_e32 v140, 1.0, v140
	v_add_f32_e32 v141, 1.0, v141
	v_add_f32_e32 v142, 1.0, v142
	v_add_f32_e32 v143, 1.0, v143
	v_add_f32_e32 v148, 1.0, v148
	v_add_f32_e32 v149, 1.0, v149
	v_add_f32_e32 v150, 1.0, v150
	v_add_f32_e32 v151, 1.0, v151
	v_add_f32_e32 v156, 1.0, v156
	v_add_f32_e32 v157, 1.0, v157
	v_add_f32_e32 v158, 1.0, v158
	v_add_f32_e32 v159, 1.0, v159
	v_rcp_f32_e32 v132, v132
	v_rcp_f32_e32 v133, v133
	v_rcp_f32_e32 v134, v134
	v_rcp_f32_e32 v135, v135
	v_rcp_f32_e32 v140, v140
	v_rcp_f32_e32 v141, v141
	v_rcp_f32_e32 v142, v142
	v_rcp_f32_e32 v143, v143
	v_rcp_f32_e32 v148, v148
	v_rcp_f32_e32 v149, v149
	v_rcp_f32_e32 v150, v150
	v_rcp_f32_e32 v151, v151
	v_rcp_f32_e32 v156, v156
	v_rcp_f32_e32 v157, v157
	v_rcp_f32_e32 v158, v158
	v_rcp_f32_e32 v159, v159
	s_nop 0
	v_mul_f32_e32 v192, v192, v100
	v_mul_f32_e32 v193, v193, v101
	v_mul_f32_e32 v194, v194, v102
	v_mul_f32_e32 v195, v195, v103
	v_mul_f32_e32 v196, v196, v108
	v_mul_f32_e32 v197, v197, v109
	v_mul_f32_e32 v198, v198, v110
	v_mul_f32_e32 v199, v199, v111
	v_mul_f32_e32 v200, v200, v116
	v_mul_f32_e32 v201, v201, v117
	v_mul_f32_e32 v202, v202, v118
	v_mul_f32_e32 v203, v203, v119
	v_mul_f32_e32 v204, v204, v124
	v_mul_f32_e32 v205, v205, v125
	v_mul_f32_e32 v206, v206, v126
	v_mul_f32_e32 v207, v207, v127
	v_mul_f32_e32 v192, v192, v132
	v_mul_f32_e32 v193, v193, v133
	v_mul_f32_e32 v194, v194, v134
	v_mul_f32_e32 v195, v195, v135
	v_mul_f32_e32 v196, v196, v140
	v_mul_f32_e32 v197, v197, v141
	v_mul_f32_e32 v198, v198, v142
	v_mul_f32_e32 v199, v199, v143
	v_mul_f32_e32 v200, v200, v148
	v_mul_f32_e32 v201, v201, v149
	v_mul_f32_e32 v202, v202, v150
	v_mul_f32_e32 v203, v203, v151
	v_mul_f32_e32 v204, v204, v156
	v_mul_f32_e32 v205, v205, v157
	v_mul_f32_e32 v206, v206, v158
	v_mul_f32_e32 v207, v207, v159
	v_cvt_pk_bf16_f32 v192, v192, v193
	v_cvt_pk_bf16_f32 v193, v194, v195
	v_cvt_pk_bf16_f32 v196, v196, v197
	v_cvt_pk_bf16_f32 v197, v198, v199
	v_cvt_pk_bf16_f32 v200, v200, v201
	v_cvt_pk_bf16_f32 v201, v202, v203
	v_cvt_pk_bf16_f32 v204, v204, v205
	v_cvt_pk_bf16_f32 v205, v206, v207
	buffer_store_dwordx2 v[192:193], v228, s[64:67], s85 offen offset:0
	buffer_store_dwordx2 v[196:197], v228, s[64:67], s85 offen offset:32
	buffer_store_dwordx2 v[200:201], v228, s[64:67], s85 offen offset:64
	buffer_store_dwordx2 v[204:205], v228, s[64:67], s85 offen offset:96
	s_add_u32 s16, s16, 1
	s_cmp_lt_u32 s16, 4
	s_cbranch_scc1 .Lmy_nat_dqt
	s_branch .Lmy_nat_next
.Lmy_nat_edge:
	s_mov_b32 s89, 2

; __device__ __forceinline__ void nat_phase(const Params& p, float* ldsf, int wave0, int nwaves) {
;     ...
;         for (int qt = 0; qt < 4; ++qt) {
;             const int c0 = qt * 16, cs0 = (qt == 0) ? 0 : (qt == 1 ? 8 : (qt == 2 ? 24 : 32));
;             const int c = c0 + l15, csq = min(max(c - 8, 0), 48);
;             const bf16x8 bq0 = *(const bf16x8*)(Qb + (size_t)c * RW + lq * 8), bq1 = *(const bf16x8*)(Qb + (size_t)c * RW + 32 + lq * 8);
;             f32x4 sc[8][2];
; #pragma unroll
;             for (int i = 0; i < 8; ++i)
; #pragma unroll
;                 for (int hf = 0; hf < 2; ++hf) { const u16* kp = Kb + (size_t)(i * 64 + cs0 + (l15 >> 2) * 8 + hf * 4 + (l15 & 3)) * RW + lq * 8;
;                     const bf16x8 a0 = *(const bf16x8*)kp, a1 = *(const bf16x8*)(kp + 32); f32x4 z = {0.f, 0.f, 0.f, 0.f};
;                     z = __builtin_amdgcn_mfma_f32_16x16x32_bf16(a0, bq0, z, 0, 0, 0); z = __builtin_amdgcn_mfma_f32_16x16x32_bf16(a1, bq1, z, 0, 0, 0); sc[i][hf] = z; }
.Lmy_nat_qt:
	s_lshl_b32 s82, s16, 4
	s_add_i32 s83, s82, -8
	s_max_i32 s83, s83, 0
	s_min_i32 s83, s83, 32
	s_lshl_b32 s84, s82, 11
	s_add_u32 s84, s84, s76
	buffer_load_dwordx4 v[192:195], v224, s[68:71], s84 offen
	buffer_load_dwordx4 v[196:199], v224, s[68:71], s84 offen offset:64
	s_lshl_b32 s84, s83, 11
	s_add_u32 s84, s84, s77
	s_add_u32 s85, s84, 0x0
	buffer_load_dwordx4 v[0:3], v225, s[68:71], s85 offen
	s_add_u32 s85, s84, 0x0
	buffer_load_dwordx4 v[4:7], v225, s[68:71], s85 offen offset:64
	s_add_u32 s85, s84, 0x2000
	buffer_load_dwordx4 v[8:11], v225, s[68:71], s85 offen
	s_add_u32 s85, s84, 0x2000
	buffer_load_dwordx4 v[12:15], v225, s[68:71], s85 offen offset:64
	s_add_u32 s85, s84, 0x20000
	buffer_load_dwordx4 v[16:19], v225, s[68:71], s85 offen
	s_add_u32 s85, s84, 0x20000
	buffer_load_dwordx4 v[20:23], v225, s[68:71], s85 offen offset:64
	s_add_u32 s85, s84, 0x22000
	buffer_load_dwordx4 v[24:27], v225, s[68:71], s85 offen
	s_add_u32 s85, s84, 0x22000
	buffer_load_dwordx4 v[28:31], v225, s[68:71], s85 offen offset:64
	v_add_u32_e32 v241, s82, v237
	v_add_u32_e32 v242, -8, v241
	v_med3_i32 v242, v242, 0, 48
	v_lshl_add_u32 v251, v238, 3, s83
	v_sub_u32_e32 v243, v251, v242
	v_sub_u32_e32 v244, v251, v241
	v_lshl_add_u32 v244, v244, 2, s3
	v_mov_b32_e32 v245, s3
	v_add_u32_e32 v245, 0x400, v245
	v_add_u32_e32 v246, 0, v243
	v_cmp_gt_u32_e32 vcc, 16, v246
	v_add_u32_e32 v247, 60, v244
	s_nop 0
	v_cndmask_b32_e32 v229, v245, v247, vcc
	v_add_u32_e32 v246, 1, v243
	v_cmp_gt_u32_e32 vcc, 16, v246
	v_add_u32_e32 v247, 64, v244
	s_nop 0
	v_cndmask_b32_e32 v230, v245, v247, vcc
	v_add_u32_e32 v246, 2, v243
	v_cmp_gt_u32_e32 vcc, 16, v246
	v_add_u32_e32 v247, 68, v244
	s_nop 0
	v_cndmask_b32_e32 v231, v245, v247, vcc
	v_add_u32_e32 v246, 3, v243
	v_cmp_gt_u32_e32 vcc, 16, v246
	v_add_u32_e32 v247, 72, v244
	s_nop 0
	v_cndmask_b32_e32 v232, v245, v247, vcc
	v_add_u32_e32 v246, 4, v243
	v_cmp_gt_u32_e32 vcc, 16, v246
	v_add_u32_e32 v247, 76, v244
	s_nop 0
	v_cndmask_b32_e32 v233, v245, v247, vcc
	v_add_u32_e32 v246, 5, v243
	v_cmp_gt_u32_e32 vcc, 16, v246
	v_add_u32_e32 v247, 80, v244
	s_nop 0
	v_cndmask_b32_e32 v234, v245, v247, vcc
	v_add_u32_e32 v246, 6, v243
	v_cmp_gt_u32_e32 vcc, 16, v246
	v_add_u32_e32 v247, 84, v244
	s_nop 0
	v_cndmask_b32_e32 v235, v245, v247, vcc
	v_add_u32_e32 v246, 7, v243
	v_cmp_gt_u32_e32 vcc, 16, v246
	v_add_u32_e32 v247, 88, v244
	s_nop 0
	v_cndmask_b32_e32 v236, v245, v247, vcc
	ds_read_b32 v128, v229 offset:0
	ds_read_b32 v129, v230 offset:0
	ds_read_b32 v130, v231 offset:0
	ds_read_b32 v131, v232 offset:0
	ds_read_b32 v132, v233 offset:0
	ds_read_b32 v133, v234 offset:0
	ds_read_b32 v134, v235 offset:0
	ds_read_b32 v135, v236 offset:0
	ds_read_b32 v136, v229 offset:124
	ds_read_b32 v137, v230 offset:124
	ds_read_b32 v138, v231 offset:124
	ds_read_b32 v139, v232 offset:124
	ds_read_b32 v140, v233 offset:124
	ds_read_b32 v141, v234 offset:124
	ds_read_b32 v142, v235 offset:124
	ds_read_b32 v143, v236 offset:124
	ds_read_b32 v144, v229 offset:248
	ds_read_b32 v145, v230 offset:248
	ds_read_b32 v146, v231 offset:248
	ds_read_b32 v147, v232 offset:248
	ds_read_b32 v148, v233 offset:248
	ds_read_b32 v149, v234 offset:248
	ds_read_b32 v150, v235 offset:248
	ds_read_b32 v151, v236 offset:248
	ds_read_b32 v152, v229 offset:372
	ds_read_b32 v153, v230 offset:372
	ds_read_b32 v154, v231 offset:372
	ds_read_b32 v155, v232 offset:372
	ds_read_b32 v156, v233 offset:372
	ds_read_b32 v157, v234 offset:372
	ds_read_b32 v158, v235 offset:372
	ds_read_b32 v159, v236 offset:372
	ds_read_b32 v160, v229 offset:496
	ds_read_b32 v161, v230 offset:496
	ds_read_b32 v162, v231 offset:496
	ds_read_b32 v163, v232 offset:496
	ds_read_b32 v164, v233 offset:496
	ds_read_b32 v165, v234 offset:496
	ds_read_b32 v166, v235 offset:496
	ds_read_b32 v167, v236 offset:496
	ds_read_b32 v168, v229 offset:620
	ds_read_b32 v169, v230 offset:620
	ds_read_b32 v170, v231 offset:620
	ds_read_b32 v171, v232 offset:620
	ds_read_b32 v172, v233 offset:620
	ds_read_b32 v173, v234 offset:620
	ds_read_b32 v174, v235 offset:620
	ds_read_b32 v175, v236 offset:620
	ds_read_b32 v176, v229 offset:744
	ds_read_b32 v177, v230 offset:744
	ds_read_b32 v178, v231 offset:744
	ds_read_b32 v179, v232 offset:744
	ds_read_b32 v180, v233 offset:744
	ds_read_b32 v181, v234 offset:744
	ds_read_b32 v182, v235 offset:744
	ds_read_b32 v183, v236 offset:744
	ds_read_b32 v184, v229 offset:868
	ds_read_b32 v185, v230 offset:868
	ds_read_b32 v186, v231 offset:868
	ds_read_b32 v187, v232 offset:868
	ds_read_b32 v188, v233 offset:868
	ds_read_b32 v189, v234 offset:868
	ds_read_b32 v190, v235 offset:868
	ds_read_b32 v191, v236 offset:868
	s_waitcnt lgkmcnt(0)
	s_add_u32 s85, s84, 0x40000
	buffer_load_dwordx4 v[32:35], v225, s[68:71], s85 offen
	s_waitcnt vmcnt(8)
	v_mfma_f32_16x16x32_bf16 v[128:131], v[0:3], v[192:195], v[128:131]
	s_add_u32 s85, s84, 0x40000
	buffer_load_dwordx4 v[36:39], v225, s[68:71], s85 offen offset:64
	s_waitcnt vmcnt(8)
	v_mfma_f32_16x16x32_bf16 v[128:131], v[4:7], v[196:199], v[128:131]
	s_add_u32 s85, s84, 0x42000
	buffer_load_dwordx4 v[40:43], v225, s[68:71], s85 offen
	s_waitcnt vmcnt(8)
	v_mfma_f32_16x16x32_bf16 v[132:135], v[8:11], v[192:195], v[132:135]
	s_add_u32 s85, s84, 0x42000
	buffer_load_dwordx4 v[44:47], v225, s[68:71], s85 offen offset:64
	s_waitcnt vmcnt(8)
	v_mfma_f32_16x16x32_bf16 v[132:135], v[12:15], v[196:199], v[132:135]
	s_add_u32 s85, s84, 0x60000
	buffer_load_dwordx4 v[48:51], v225, s[68:71], s85 offen
	s_waitcnt vmcnt(8)
	v_mfma_f32_16x16x32_bf16 v[136:139], v[16:19], v[192:195], v[136:139]
	s_add_u32 s85, s84, 0x60000
	buffer_load_dwordx4 v[52:55], v225, s[68:71], s85 offen offset:64
	s_waitcnt vmcnt(8)
; __device__ __forceinline__ void nat_phase(const Params& p, float* ldsf, int wave0, int nwaves) {
;     ...
;             for (int i = 0; i < 8; ++i)
; #pragma unroll
;                 for (int hf = 0; hf < 2; ++hf) { const u16* kp = Kb + (size_t)(i * 64 + cs0 + (l15 >> 2) * 8 + hf * 4 + (l15 & 3)) * RW + lq * 8;
;                     const bf16x8 a0 = *(const bf16x8*)kp, a1 = *(const bf16x8*)(kp + 32); f32x4 z = {0.f, 0.f, 0.f, 0.f};
;                     z = __builtin_amdgcn_mfma_f32_16x16x32_bf16(a0, bq0, z, 0, 0, 0); z = __builtin_amdgcn_mfma_f32_16x16x32_bf16(a1, bq1, z, 0, 0, 0); sc[i][hf] = z; }
;             float mx = -1e30f;
; #pragma unroll
;             for (int i = 0; i < 8; ++i)
; #pragma unroll
;                 for (int hf = 0; hf < 2; ++hf)
; #pragma unroll
;                     for (int j = 0; j < 4; ++j) { const int kc = cs0 + lq * 8 + hf * 4 + j; const bool valid = (kc >= csq) && (kc < csq + 16); const int bc = valid ? (kc - c + 15) : 0;
;                         const float s = valid ? sc[i][hf][j] * 0.125f + tb[i * 31 + bc] : -1e30f; sc[i][hf][j] = s; mx = fmaxf(mx, s); }
;             mx = fmaxf(mx, __shfl_xor(mx, 16)); mx = fmaxf(mx, __shfl_xor(mx, 32));
	v_mfma_f32_16x16x32_bf16 v[136:139], v[20:23], v[196:199], v[136:139]
	s_add_u32 s85, s84, 0x62000
	buffer_load_dwordx4 v[56:59], v225, s[68:71], s85 offen
	s_waitcnt vmcnt(8)
	v_mfma_f32_16x16x32_bf16 v[140:143], v[24:27], v[192:195], v[140:143]
	s_add_u32 s85, s84, 0x62000
	buffer_load_dwordx4 v[60:63], v225, s[68:71], s85 offen offset:64
	s_waitcnt vmcnt(8)
	v_mfma_f32_16x16x32_bf16 v[140:143], v[28:31], v[196:199], v[140:143]
	s_add_u32 s85, s84, 0x80000
	buffer_load_dwordx4 v[64:67], v225, s[68:71], s85 offen
	s_waitcnt vmcnt(8)
	v_mfma_f32_16x16x32_bf16 v[144:147], v[32:35], v[192:195], v[144:147]
	s_add_u32 s85, s84, 0x80000
	buffer_load_dwordx4 v[68:71], v225, s[68:71], s85 offen offset:64
	s_waitcnt vmcnt(8)
	v_mfma_f32_16x16x32_bf16 v[144:147], v[36:39], v[196:199], v[144:147]
	s_add_u32 s85, s84, 0x82000
	buffer_load_dwordx4 v[72:75], v225, s[68:71], s85 offen
	s_waitcnt vmcnt(8)
	v_mfma_f32_16x16x32_bf16 v[148:151], v[40:43], v[192:195], v[148:151]
	s_add_u32 s85, s84, 0x82000
	buffer_load_dwordx4 v[76:79], v225, s[68:71], s85 offen offset:64
	s_waitcnt vmcnt(8)
	v_mfma_f32_16x16x32_bf16 v[148:151], v[44:47], v[196:199], v[148:151]
	s_add_u32 s85, s84, 0xa0000
	buffer_load_dwordx4 v[80:83], v225, s[68:71], s85 offen
	s_waitcnt vmcnt(8)
	v_mfma_f32_16x16x32_bf16 v[152:155], v[48:51], v[192:195], v[152:155]
	s_add_u32 s85, s84, 0xa0000
	buffer_load_dwordx4 v[84:87], v225, s[68:71], s85 offen offset:64
	s_waitcnt vmcnt(8)
	v_mfma_f32_16x16x32_bf16 v[152:155], v[52:55], v[196:199], v[152:155]
	s_add_u32 s85, s84, 0xa2000
	buffer_load_dwordx4 v[88:91], v225, s[68:71], s85 offen
	s_waitcnt vmcnt(8)
	v_mfma_f32_16x16x32_bf16 v[156:159], v[56:59], v[192:195], v[156:159]
	s_add_u32 s85, s84, 0xa2000
	buffer_load_dwordx4 v[92:95], v225, s[68:71], s85 offen offset:64
	s_waitcnt vmcnt(8)
	v_mfma_f32_16x16x32_bf16 v[156:159], v[60:63], v[196:199], v[156:159]
	s_add_u32 s85, s84, 0xc0000
	buffer_load_dwordx4 v[96:99], v225, s[68:71], s85 offen
	s_waitcnt vmcnt(8)
	v_mfma_f32_16x16x32_bf16 v[160:163], v[64:67], v[192:195], v[160:163]
	s_add_u32 s85, s84, 0xc0000
	buffer_load_dwordx4 v[100:103], v225, s[68:71], s85 offen offset:64
	s_waitcnt vmcnt(8)
	v_mfma_f32_16x16x32_bf16 v[160:163], v[68:71], v[196:199], v[160:163]
	s_add_u32 s85, s84, 0xc2000
	buffer_load_dwordx4 v[104:107], v225, s[68:71], s85 offen
	s_waitcnt vmcnt(8)
	v_mfma_f32_16x16x32_bf16 v[164:167], v[72:75], v[192:195], v[164:167]
	s_add_u32 s85, s84, 0xc2000
	buffer_load_dwordx4 v[108:111], v225, s[68:71], s85 offen offset:64
	s_waitcnt vmcnt(8)
	v_mfma_f32_16x16x32_bf16 v[164:167], v[76:79], v[196:199], v[164:167]
	s_add_u32 s85, s84, 0xe0000
	buffer_load_dwordx4 v[112:115], v225, s[68:71], s85 offen
	s_waitcnt vmcnt(8)
	v_mfma_f32_16x16x32_bf16 v[168:171], v[80:83], v[192:195], v[168:171]
	s_add_u32 s85, s84, 0xe0000
	buffer_load_dwordx4 v[116:119], v225, s[68:71], s85 offen offset:64
	s_waitcnt vmcnt(8)
	v_mfma_f32_16x16x32_bf16 v[168:171], v[84:87], v[196:199], v[168:171]
	s_add_u32 s85, s84, 0xe2000
	buffer_load_dwordx4 v[120:123], v225, s[68:71], s85 offen
	s_waitcnt vmcnt(8)
	v_mfma_f32_16x16x32_bf16 v[172:175], v[88:91], v[192:195], v[172:175]
	s_add_u32 s85, s84, 0xe2000
	buffer_load_dwordx4 v[124:127], v225, s[68:71], s85 offen offset:64
	s_waitcnt vmcnt(8)
	v_mfma_f32_16x16x32_bf16 v[172:175], v[92:95], v[196:199], v[172:175]
	s_waitcnt vmcnt(7)
	v_mfma_f32_16x16x32_bf16 v[176:179], v[96:99], v[192:195], v[176:179]
	s_waitcnt vmcnt(6)
	v_mfma_f32_16x16x32_bf16 v[176:179], v[100:103], v[196:199], v[176:179]
	s_waitcnt vmcnt(5)
	v_mfma_f32_16x16x32_bf16 v[180:183], v[104:107], v[192:195], v[180:183]
	s_waitcnt vmcnt(4)
	v_mfma_f32_16x16x32_bf16 v[180:183], v[108:111], v[196:199], v[180:183]
	s_waitcnt vmcnt(3)
	v_mfma_f32_16x16x32_bf16 v[184:187], v[112:115], v[192:195], v[184:187]
	s_waitcnt vmcnt(2)
	v_mfma_f32_16x16x32_bf16 v[184:187], v[116:119], v[196:199], v[184:187]
	s_waitcnt vmcnt(1)
	v_mfma_f32_16x16x32_bf16 v[188:191], v[120:123], v[192:195], v[188:191]
	s_waitcnt vmcnt(0)
	v_mfma_f32_16x16x32_bf16 v[188:191], v[124:127], v[196:199], v[188:191]
	s_lshl_b32 s84, s82, 11
	s_add_u32 s84, s84, s79
	buffer_load_dwordx2 v[216:217], v227, s[68:71], s84 offen offset:0
	buffer_load_dwordx2 v[218:219], v227, s[68:71], s84 offen offset:32
	buffer_load_dwordx2 v[220:221], v227, s[68:71], s84 offen offset:64
	buffer_load_dwordx2 v[222:223], v227, s[68:71], s84 offen offset:96
	s_lshl_b32 s84, s83, 1
	s_add_u32 s84, s84, s78
	s_add_u32 s85, s84, 0x80000
	s_add_u32 s86, s84, 0x100000
	s_add_u32 s87, s84, 0x180000
	buffer_load_dwordx4 v[0:3], v226, s[68:71], s84 offen offset:0
	buffer_load_dwordx4 v[4:7], v226, s[68:71], s85 offen offset:0
	buffer_load_dwordx4 v[8:11], v226, s[68:71], s86 offen offset:0
	buffer_load_dwordx4 v[12:15], v226, s[68:71], s87 offen offset:0
	buffer_load_dwordx4 v[16:19], v226, s[68:71], s84 offen offset:128
	buffer_load_dwordx4 v[20:23], v226, s[68:71], s85 offen offset:128
	buffer_load_dwordx4 v[24:27], v226, s[68:71], s86 offen offset:128
	buffer_load_dwordx4 v[28:31], v226, s[68:71], s87 offen offset:128
	v_max3_f32 v239, v128, v129, v130
	v_max3_f32 v239, v239, v131, v132
	v_max3_f32 v239, v239, v133, v134
	v_max3_f32 v239, v239, v135, v136
	v_max3_f32 v239, v239, v137, v138
	v_max3_f32 v239, v239, v139, v140
	v_max3_f32 v239, v239, v141, v142
	v_max3_f32 v239, v239, v143, v144
	v_max3_f32 v239, v239, v145, v146
	v_max3_f32 v239, v239, v147, v148
	v_max3_f32 v239, v239, v149, v150
	v_max3_f32 v239, v239, v151, v152
	v_max3_f32 v239, v239, v153, v154
	v_max3_f32 v239, v239, v155, v156
	v_max3_f32 v239, v239, v157, v158
	v_max3_f32 v239, v239, v159, v160
	v_max3_f32 v239, v239, v161, v162
	v_max3_f32 v239, v239, v163, v164
	v_max3_f32 v239, v239, v165, v166
	v_max3_f32 v239, v239, v167, v168
	v_max3_f32 v239, v239, v169, v170
	v_max3_f32 v239, v239, v171, v172
	v_max3_f32 v239, v239, v173, v174
	v_max3_f32 v239, v239, v175, v176
	v_max3_f32 v239, v239, v177, v178
	v_max3_f32 v239, v239, v179, v180
	v_max3_f32 v239, v239, v181, v182
	v_max3_f32 v239, v239, v183, v184
	v_max3_f32 v239, v239, v185, v186
	v_max3_f32 v239, v239, v187, v188
	v_max3_f32 v239, v239, v189, v190
	v_max_f32_e32 v239, v239, v191
	ds_bpermute_b32 v242, v248, v239
	s_waitcnt lgkmcnt(0)
; __device__ __forceinline__ void nat_phase(const Params& p, float* ldsf, int wave0, int nwaves) {
;     ...
;             mx = fmaxf(mx, __shfl_xor(mx, 16)); mx = fmaxf(mx, __shfl_xor(mx, 32));
;             float sum = 0.f;
; #pragma unroll
;             for (int i = 0; i < 8; ++i)
; #pragma unroll
;                 for (int hf = 0; hf < 2; ++hf)
; #pragma unroll
;                     for (int j = 0; j < 4; ++j) { const float e = __expf(sc[i][hf][j] - mx); sc[i][hf][j] = e; sum += e; }
;             sum += __shfl_xor(sum, 16); sum += __shfl_xor(sum, 32);
	v_max_f32_e32 v239, v239, v242
	ds_bpermute_b32 v242, v249, v239
	s_waitcnt lgkmcnt(0)
	v_max_f32_e32 v239, v239, v242
	v_mul_f32_e64 v242, -v239, v252
	v_mov_b32_e32 v243, v242
	v_pk_fma_f32 v[128:129], v[128:129], v[252:253], v[242:243]
	v_pk_fma_f32 v[130:131], v[130:131], v[252:253], v[242:243]
	v_pk_fma_f32 v[132:133], v[132:133], v[252:253], v[242:243]
	v_pk_fma_f32 v[134:135], v[134:135], v[252:253], v[242:243]
	v_pk_fma_f32 v[136:137], v[136:137], v[252:253], v[242:243]
	v_pk_fma_f32 v[138:139], v[138:139], v[252:253], v[242:243]
	v_pk_fma_f32 v[140:141], v[140:141], v[252:253], v[242:243]
	v_pk_fma_f32 v[142:143], v[142:143], v[252:253], v[242:243]
	v_pk_fma_f32 v[144:145], v[144:145], v[252:253], v[242:243]
	v_pk_fma_f32 v[146:147], v[146:147], v[252:253], v[242:243]
	v_pk_fma_f32 v[148:149], v[148:149], v[252:253], v[242:243]
	v_pk_fma_f32 v[150:151], v[150:151], v[252:253], v[242:243]
	v_pk_fma_f32 v[152:153], v[152:153], v[252:253], v[242:243]
	v_pk_fma_f32 v[154:155], v[154:155], v[252:253], v[242:243]
	v_pk_fma_f32 v[156:157], v[156:157], v[252:253], v[242:243]
	v_pk_fma_f32 v[158:159], v[158:159], v[252:253], v[242:243]
	v_pk_fma_f32 v[160:161], v[160:161], v[252:253], v[242:243]
	v_pk_fma_f32 v[162:163], v[162:163], v[252:253], v[242:243]
	v_pk_fma_f32 v[164:165], v[164:165], v[252:253], v[242:243]
	v_pk_fma_f32 v[166:167], v[166:167], v[252:253], v[242:243]
	v_pk_fma_f32 v[168:169], v[168:169], v[252:253], v[242:243]
	v_pk_fma_f32 v[170:171], v[170:171], v[252:253], v[242:243]
	v_pk_fma_f32 v[172:173], v[172:173], v[252:253], v[242:243]
	v_pk_fma_f32 v[174:175], v[174:175], v[252:253], v[242:243]
	v_pk_fma_f32 v[176:177], v[176:177], v[252:253], v[242:243]
	v_pk_fma_f32 v[178:179], v[178:179], v[252:253], v[242:243]
	v_pk_fma_f32 v[180:181], v[180:181], v[252:253], v[242:243]
	v_pk_fma_f32 v[182:183], v[182:183], v[252:253], v[242:243]
	v_pk_fma_f32 v[184:185], v[184:185], v[252:253], v[242:243]
	v_pk_fma_f32 v[186:187], v[186:187], v[252:253], v[242:243]
	v_pk_fma_f32 v[188:189], v[188:189], v[252:253], v[242:243]
	v_pk_fma_f32 v[190:191], v[190:191], v[252:253], v[242:243]
	v_exp_f32_e32 v128, v128
	v_exp_f32_e32 v129, v129
	v_exp_f32_e32 v130, v130
	v_exp_f32_e32 v131, v131
	v_exp_f32_e32 v132, v132
	v_exp_f32_e32 v133, v133
	v_exp_f32_e32 v134, v134
	v_exp_f32_e32 v135, v135
	v_exp_f32_e32 v136, v136
	v_exp_f32_e32 v137, v137
	v_exp_f32_e32 v138, v138
	v_exp_f32_e32 v139, v139
	v_exp_f32_e32 v140, v140
	v_exp_f32_e32 v141, v141
	v_exp_f32_e32 v142, v142
	v_exp_f32_e32 v143, v143
	v_exp_f32_e32 v144, v144
	v_exp_f32_e32 v145, v145
	v_exp_f32_e32 v146, v146
	v_exp_f32_e32 v147, v147
	v_exp_f32_e32 v148, v148
	v_exp_f32_e32 v149, v149
	v_exp_f32_e32 v150, v150
	v_exp_f32_e32 v151, v151
	v_exp_f32_e32 v152, v152
	v_exp_f32_e32 v153, v153
	v_exp_f32_e32 v154, v154
	v_exp_f32_e32 v155, v155
	v_exp_f32_e32 v156, v156
	v_exp_f32_e32 v157, v157
	v_exp_f32_e32 v158, v158
	v_exp_f32_e32 v159, v159
	v_exp_f32_e32 v160, v160
	v_exp_f32_e32 v161, v161
	v_exp_f32_e32 v162, v162
	v_exp_f32_e32 v163, v163
	v_exp_f32_e32 v164, v164
	v_exp_f32_e32 v165, v165
	v_exp_f32_e32 v166, v166
	v_exp_f32_e32 v167, v167
	v_exp_f32_e32 v168, v168
	v_exp_f32_e32 v169, v169
	v_exp_f32_e32 v170, v170
	v_exp_f32_e32 v171, v171
	v_exp_f32_e32 v172, v172
	v_exp_f32_e32 v173, v173
	v_exp_f32_e32 v174, v174
	v_exp_f32_e32 v175, v175
	v_exp_f32_e32 v176, v176
	v_exp_f32_e32 v177, v177
	v_exp_f32_e32 v178, v178
	v_exp_f32_e32 v179, v179
	v_exp_f32_e32 v180, v180
	v_exp_f32_e32 v181, v181
	v_exp_f32_e32 v182, v182
	v_exp_f32_e32 v183, v183
	v_exp_f32_e32 v184, v184
	v_exp_f32_e32 v185, v185
	v_exp_f32_e32 v186, v186
	v_exp_f32_e32 v187, v187
	v_exp_f32_e32 v188, v188
	v_exp_f32_e32 v189, v189
	v_exp_f32_e32 v190, v190
	v_exp_f32_e32 v191, v191
	s_nop 0
	v_pk_add_f32 v[244:245], v[128:129], v[130:131]
	v_pk_add_f32 v[246:247], v[132:133], v[134:135]
	v_pk_add_f32 v[244:245], v[244:245], v[136:137]
	v_pk_add_f32 v[246:247], v[246:247], v[138:139]
	v_pk_add_f32 v[244:245], v[244:245], v[140:141]
	v_pk_add_f32 v[246:247], v[246:247], v[142:143]
	v_pk_add_f32 v[244:245], v[244:245], v[144:145]
	v_pk_add_f32 v[246:247], v[246:247], v[146:147]
	v_pk_add_f32 v[244:245], v[244:245], v[148:149]
	v_pk_add_f32 v[246:247], v[246:247], v[150:151]
	v_pk_add_f32 v[244:245], v[244:245], v[152:153]
	v_pk_add_f32 v[246:247], v[246:247], v[154:155]
	v_pk_add_f32 v[244:245], v[244:245], v[156:157]
	v_pk_add_f32 v[246:247], v[246:247], v[158:159]
	v_pk_add_f32 v[244:245], v[244:245], v[160:161]
	v_pk_add_f32 v[246:247], v[246:247], v[162:163]
	v_pk_add_f32 v[244:245], v[244:245], v[164:165]
	v_pk_add_f32 v[246:247], v[246:247], v[166:167]
	v_pk_add_f32 v[244:245], v[244:245], v[168:169]
	v_pk_add_f32 v[246:247], v[246:247], v[170:171]
	v_pk_add_f32 v[244:245], v[244:245], v[172:173]
	v_pk_add_f32 v[246:247], v[246:247], v[174:175]
	v_pk_add_f32 v[244:245], v[244:245], v[176:177]
	v_pk_add_f32 v[246:247], v[246:247], v[178:179]
	v_pk_add_f32 v[244:245], v[244:245], v[180:181]
	v_pk_add_f32 v[246:247], v[246:247], v[182:183]
	v_pk_add_f32 v[244:245], v[244:245], v[184:185]
	v_pk_add_f32 v[246:247], v[246:247], v[186:187]
	v_pk_add_f32 v[244:245], v[244:245], v[188:189]
	v_pk_add_f32 v[246:247], v[246:247], v[190:191]
	v_pk_add_f32 v[244:245], v[244:245], v[246:247]
	v_add_f32_e32 v240, v244, v245
	ds_bpermute_b32 v242, v248, v240
	s_waitcnt lgkmcnt(0)
	v_add_f32_e32 v240, v240, v242
	ds_bpermute_b32 v242, v249, v240
	s_waitcnt lgkmcnt(0)
; __device__ __forceinline__ unsigned cvt_pk_bf16(float lo, float hi) { unsigned r; asm volatile("v_cvt_pk_bf16_f32 %0, %1, %2" : "=v"(r) : "v"(lo), "v"(hi)); return r; }
; __device__ __forceinline__ void nat_phase(const Params& p, float* ldsf, int wave0, int nwaves) {
;     ...
;             const float inv = 1.0f / sum;
;             f32x4 o[4];
; #pragma unroll
;             for (int mt = 0; mt < 4; ++mt) o[mt] = (f32x4){0.f, 0.f, 0.f, 0.f};
; #pragma unroll
;             for (int i = 0; i < 8; ++i) {
;                 u32x4 pw; pw.x = cvt_pk_bf16(sc[i][0][0] * inv, sc[i][0][1] * inv); pw.y = cvt_pk_bf16(sc[i][0][2] * inv, sc[i][0][3] * inv);
;                 pw.z = cvt_pk_bf16(sc[i][1][0] * inv, sc[i][1][1] * inv); pw.w = cvt_pk_bf16(sc[i][1][2] * inv, sc[i][1][3] * inv);
;                 const bf16x8 bp = __builtin_bit_cast(bf16x8, pw);
; #pragma unroll
;                 for (int mt = 0; mt < 4; ++mt) { const u16* vp = Vb + (size_t)(mt * 16 + l15) * SEQ + i * 64 + cs0 + lq * 8;
;                     o[mt] = __builtin_amdgcn_mfma_f32_16x16x32_bf16(*(const bf16x8*)vp, bp, o[mt], 0, 0, 0); }
;             }
	v_add_f32_e32 v240, v240, v242
	v_rcp_f32_e32 v242, v240
	s_nop 0
	v_mov_b32_e32 v243, v242
	v_pk_mul_f32 v[128:129], v[128:129], v[242:243]
	v_pk_mul_f32 v[130:131], v[130:131], v[242:243]
	v_pk_mul_f32 v[132:133], v[132:133], v[242:243]
	v_pk_mul_f32 v[134:135], v[134:135], v[242:243]
	v_pk_mul_f32 v[136:137], v[136:137], v[242:243]
	v_pk_mul_f32 v[138:139], v[138:139], v[242:243]
	v_pk_mul_f32 v[140:141], v[140:141], v[242:243]
	v_pk_mul_f32 v[142:143], v[142:143], v[242:243]
	v_pk_mul_f32 v[144:145], v[144:145], v[242:243]
	v_pk_mul_f32 v[146:147], v[146:147], v[242:243]
	v_pk_mul_f32 v[148:149], v[148:149], v[242:243]
	v_pk_mul_f32 v[150:151], v[150:151], v[242:243]
	v_pk_mul_f32 v[152:153], v[152:153], v[242:243]
	v_pk_mul_f32 v[154:155], v[154:155], v[242:243]
	v_pk_mul_f32 v[156:157], v[156:157], v[242:243]
	v_pk_mul_f32 v[158:159], v[158:159], v[242:243]
	v_pk_mul_f32 v[160:161], v[160:161], v[242:243]
	v_pk_mul_f32 v[162:163], v[162:163], v[242:243]
	v_pk_mul_f32 v[164:165], v[164:165], v[242:243]
	v_pk_mul_f32 v[166:167], v[166:167], v[242:243]
	v_pk_mul_f32 v[168:169], v[168:169], v[242:243]
	v_pk_mul_f32 v[170:171], v[170:171], v[242:243]
	v_pk_mul_f32 v[172:173], v[172:173], v[242:243]
	v_pk_mul_f32 v[174:175], v[174:175], v[242:243]
	v_pk_mul_f32 v[176:177], v[176:177], v[242:243]
	v_pk_mul_f32 v[178:179], v[178:179], v[242:243]
	v_pk_mul_f32 v[180:181], v[180:181], v[242:243]
	v_pk_mul_f32 v[182:183], v[182:183], v[242:243]
	v_pk_mul_f32 v[184:185], v[184:185], v[242:243]
	v_pk_mul_f32 v[186:187], v[186:187], v[242:243]
	v_pk_mul_f32 v[188:189], v[188:189], v[242:243]
	v_pk_mul_f32 v[190:191], v[190:191], v[242:243]
	v_cvt_pk_bf16_f32 v128, v128, v129
	v_cvt_pk_bf16_f32 v129, v130, v131
	v_cvt_pk_bf16_f32 v130, v132, v133
	v_cvt_pk_bf16_f32 v131, v134, v135
	v_cvt_pk_bf16_f32 v136, v136, v137
	v_cvt_pk_bf16_f32 v137, v138, v139
	v_cvt_pk_bf16_f32 v138, v140, v141
	v_cvt_pk_bf16_f32 v139, v142, v143
	v_cvt_pk_bf16_f32 v144, v144, v145
	v_cvt_pk_bf16_f32 v145, v146, v147
	v_cvt_pk_bf16_f32 v146, v148, v149
	v_cvt_pk_bf16_f32 v147, v150, v151
	v_cvt_pk_bf16_f32 v152, v152, v153
	v_cvt_pk_bf16_f32 v153, v154, v155
	v_cvt_pk_bf16_f32 v154, v156, v157
	v_cvt_pk_bf16_f32 v155, v158, v159
	v_cvt_pk_bf16_f32 v160, v160, v161
	v_cvt_pk_bf16_f32 v161, v162, v163
	v_cvt_pk_bf16_f32 v162, v164, v165
	v_cvt_pk_bf16_f32 v163, v166, v167
	v_cvt_pk_bf16_f32 v168, v168, v169
	v_cvt_pk_bf16_f32 v169, v170, v171
	v_cvt_pk_bf16_f32 v170, v172, v173
	v_cvt_pk_bf16_f32 v171, v174, v175
	v_cvt_pk_bf16_f32 v176, v176, v177
	v_cvt_pk_bf16_f32 v177, v178, v179
	v_cvt_pk_bf16_f32 v178, v180, v181
	v_cvt_pk_bf16_f32 v179, v182, v183
	v_cvt_pk_bf16_f32 v184, v184, v185
	v_cvt_pk_bf16_f32 v185, v186, v187
	v_cvt_pk_bf16_f32 v186, v188, v189
	v_cvt_pk_bf16_f32 v187, v190, v191
	buffer_load_dwordx4 v[32:35], v226, s[68:71], s84 offen offset:256
	s_waitcnt vmcnt(8)
	v_mfma_f32_16x16x32_bf16 v[200:203], v[0:3], v[128:131], 0
	buffer_load_dwordx4 v[36:39], v226, s[68:71], s85 offen offset:256
	s_waitcnt vmcnt(8)
	v_mfma_f32_16x16x32_bf16 v[204:207], v[4:7], v[128:131], 0
	buffer_load_dwordx4 v[40:43], v226, s[68:71], s86 offen offset:256
	s_waitcnt vmcnt(8)
	v_mfma_f32_16x16x32_bf16 v[208:211], v[8:11], v[128:131], 0
	buffer_load_dwordx4 v[44:47], v226, s[68:71], s87 offen offset:256
	s_waitcnt vmcnt(8)
	v_mfma_f32_16x16x32_bf16 v[212:215], v[12:15], v[128:131], 0
	buffer_load_dwordx4 v[48:51], v226, s[68:71], s84 offen offset:384
	s_waitcnt vmcnt(8)
	v_mfma_f32_16x16x32_bf16 v[200:203], v[16:19], v[136:139], v[200:203]
	buffer_load_dwordx4 v[52:55], v226, s[68:71], s85 offen offset:384
	s_waitcnt vmcnt(8)
	v_mfma_f32_16x16x32_bf16 v[204:207], v[20:23], v[136:139], v[204:207]
	buffer_load_dwordx4 v[56:59], v226, s[68:71], s86 offen offset:384
	s_waitcnt vmcnt(8)
	v_mfma_f32_16x16x32_bf16 v[208:211], v[24:27], v[136:139], v[208:211]
	buffer_load_dwordx4 v[60:63], v226, s[68:71], s87 offen offset:384
	s_waitcnt vmcnt(8)
	v_mfma_f32_16x16x32_bf16 v[212:215], v[28:31], v[136:139], v[212:215]
	buffer_load_dwordx4 v[64:67], v226, s[68:71], s84 offen offset:512
	s_waitcnt vmcnt(8)
	v_mfma_f32_16x16x32_bf16 v[200:203], v[32:35], v[144:147], v[200:203]
	buffer_load_dwordx4 v[68:71], v226, s[68:71], s85 offen offset:512
	s_waitcnt vmcnt(8)
	v_mfma_f32_16x16x32_bf16 v[204:207], v[36:39], v[144:147], v[204:207]
	buffer_load_dwordx4 v[72:75], v226, s[68:71], s86 offen offset:512
	s_waitcnt vmcnt(8)
	v_mfma_f32_16x16x32_bf16 v[208:211], v[40:43], v[144:147], v[208:211]
	buffer_load_dwordx4 v[76:79], v226, s[68:71], s87 offen offset:512
	s_waitcnt vmcnt(8)
	v_mfma_f32_16x16x32_bf16 v[212:215], v[44:47], v[144:147], v[212:215]
	buffer_load_dwordx4 v[80:83], v226, s[68:71], s84 offen offset:640
	s_waitcnt vmcnt(8)
	v_mfma_f32_16x16x32_bf16 v[200:203], v[48:51], v[152:155], v[200:203]
	buffer_load_dwordx4 v[84:87], v226, s[68:71], s85 offen offset:640
	s_waitcnt vmcnt(8)
	v_mfma_f32_16x16x32_bf16 v[204:207], v[52:55], v[152:155], v[204:207]
	buffer_load_dwordx4 v[88:91], v226, s[68:71], s86 offen offset:640
	s_waitcnt vmcnt(8)
	v_mfma_f32_16x16x32_bf16 v[208:211], v[56:59], v[152:155], v[208:211]
	buffer_load_dwordx4 v[92:95], v226, s[68:71], s87 offen offset:640
	s_waitcnt vmcnt(8)
	v_mfma_f32_16x16x32_bf16 v[212:215], v[60:63], v[152:155], v[212:215]
	buffer_load_dwordx4 v[96:99], v226, s[68:71], s84 offen offset:768
	s_waitcnt vmcnt(8)
	v_mfma_f32_16x16x32_bf16 v[200:203], v[64:67], v[160:163], v[200:203]
	buffer_load_dwordx4 v[100:103], v226, s[68:71], s85 offen offset:768
	s_waitcnt vmcnt(8)
; __device__ __forceinline__ float bflo(unsigned w) { return __uint_as_float(w << 16); }
; __device__ __forceinline__ float bfhi(unsigned w) { return __uint_as_float(w & 0xffff0000u); }
; __device__ __forceinline__ unsigned cvt_pk_bf16(float lo, float hi) { unsigned r; asm volatile("v_cvt_pk_bf16_f32 %0, %1, %2" : "=v"(r) : "v"(lo), "v"(hi)); return r; }
; __device__ __forceinline__ float sigmoidf_(float x) { return __builtin_amdgcn_rcpf(1.0f + __expf(-x)); }
; __device__ __forceinline__ void nat_phase(const Params& p, float* ldsf, int wave0, int nwaves) {
;     ...
;                 for (int mt = 0; mt < 4; ++mt) { const u16* vp = Vb + (size_t)(mt * 16 + l15) * SEQ + i * 64 + cs0 + lq * 8;
;                     o[mt] = __builtin_amdgcn_mfma_f32_16x16x32_bf16(*(const bf16x8*)vp, bp, o[mt], 0, 0, 0); }
;             }
;             const size_t tok = (size_t)(b * SEQ + r * 64 + c);
; #pragma unroll
;             for (int mt = 0; mt < 4; ++mt) { const int ch = h * 64 + mt * 16 + lq * 4; const u32x2 gw = *(const u32x2*)(Gn + tok * RW + ch);
;                 const float g0 = bflo(gw.x), g1 = bfhi(gw.x), g2 = bflo(gw.y), g3 = bfhi(gw.y);
;                 u32x2 w; w.x = cvt_pk_bf16(o[mt][0] * g0 * sigmoidf_(g0), o[mt][1] * g1 * sigmoidf_(g1)); w.y = cvt_pk_bf16(o[mt][2] * g2 * sigmoidf_(g2), o[mt][3] * g3 * sigmoidf_(g3));
;                 *(u32x2*)(MIX + tok * DM + 1024 + ch) = w; }
;         }
;     }
	v_mfma_f32_16x16x32_bf16 v[204:207], v[68:71], v[160:163], v[204:207]
	buffer_load_dwordx4 v[104:107], v226, s[68:71], s86 offen offset:768
	s_waitcnt vmcnt(8)
	v_mfma_f32_16x16x32_bf16 v[208:211], v[72:75], v[160:163], v[208:211]
	buffer_load_dwordx4 v[108:111], v226, s[68:71], s87 offen offset:768
	s_waitcnt vmcnt(8)
	v_mfma_f32_16x16x32_bf16 v[212:215], v[76:79], v[160:163], v[212:215]
	buffer_load_dwordx4 v[112:115], v226, s[68:71], s84 offen offset:896
	s_waitcnt vmcnt(8)
	v_mfma_f32_16x16x32_bf16 v[200:203], v[80:83], v[168:171], v[200:203]
	buffer_load_dwordx4 v[116:119], v226, s[68:71], s85 offen offset:896
	s_waitcnt vmcnt(8)
	v_mfma_f32_16x16x32_bf16 v[204:207], v[84:87], v[168:171], v[204:207]
	buffer_load_dwordx4 v[120:123], v226, s[68:71], s86 offen offset:896
	s_waitcnt vmcnt(8)
	v_mfma_f32_16x16x32_bf16 v[208:211], v[88:91], v[168:171], v[208:211]
	buffer_load_dwordx4 v[124:127], v226, s[68:71], s87 offen offset:896
	s_waitcnt vmcnt(8)
	v_mfma_f32_16x16x32_bf16 v[212:215], v[92:95], v[168:171], v[212:215]
	s_waitcnt vmcnt(7)
	v_mfma_f32_16x16x32_bf16 v[200:203], v[96:99], v[176:179], v[200:203]
	s_waitcnt vmcnt(6)
	v_mfma_f32_16x16x32_bf16 v[204:207], v[100:103], v[176:179], v[204:207]
	s_waitcnt vmcnt(5)
	v_mfma_f32_16x16x32_bf16 v[208:211], v[104:107], v[176:179], v[208:211]
	s_waitcnt vmcnt(4)
	v_mfma_f32_16x16x32_bf16 v[212:215], v[108:111], v[176:179], v[212:215]
	s_waitcnt vmcnt(3)
	v_mfma_f32_16x16x32_bf16 v[200:203], v[112:115], v[184:187], v[200:203]
	s_waitcnt vmcnt(2)
	v_mfma_f32_16x16x32_bf16 v[204:207], v[116:119], v[184:187], v[204:207]
	s_waitcnt vmcnt(1)
	v_mfma_f32_16x16x32_bf16 v[208:211], v[120:123], v[184:187], v[208:211]
	s_waitcnt vmcnt(0)
	v_mfma_f32_16x16x32_bf16 v[212:215], v[124:127], v[184:187], v[212:215]
	s_waitcnt vmcnt(0)
	s_lshl_b32 s84, s82, 12
	s_add_u32 s84, s84, s80
	v_lshlrev_b32_e32 v132, 16, v216
	v_and_b32_e32 v133, 0xffff0000, v216
	v_lshlrev_b32_e32 v134, 16, v217
	v_and_b32_e32 v135, 0xffff0000, v217
	v_lshlrev_b32_e32 v140, 16, v218
	v_and_b32_e32 v141, 0xffff0000, v218
	v_lshlrev_b32_e32 v142, 16, v219
	v_and_b32_e32 v143, 0xffff0000, v219
	v_lshlrev_b32_e32 v148, 16, v220
	v_and_b32_e32 v149, 0xffff0000, v220
	v_lshlrev_b32_e32 v150, 16, v221
	v_and_b32_e32 v151, 0xffff0000, v221
	v_lshlrev_b32_e32 v156, 16, v222
	v_and_b32_e32 v157, 0xffff0000, v222
	v_lshlrev_b32_e32 v158, 16, v223
	v_and_b32_e32 v159, 0xffff0000, v223
	v_mul_f32_e32 v164, 0xbfb8aa3b, v132
	v_mul_f32_e32 v165, 0xbfb8aa3b, v133
	v_mul_f32_e32 v166, 0xbfb8aa3b, v134
	v_mul_f32_e32 v167, 0xbfb8aa3b, v135
	v_mul_f32_e32 v172, 0xbfb8aa3b, v140
	v_mul_f32_e32 v173, 0xbfb8aa3b, v141
	v_mul_f32_e32 v174, 0xbfb8aa3b, v142
	v_mul_f32_e32 v175, 0xbfb8aa3b, v143
	v_mul_f32_e32 v180, 0xbfb8aa3b, v148
	v_mul_f32_e32 v181, 0xbfb8aa3b, v149
	v_mul_f32_e32 v182, 0xbfb8aa3b, v150
	v_mul_f32_e32 v183, 0xbfb8aa3b, v151
	v_mul_f32_e32 v188, 0xbfb8aa3b, v156
	v_mul_f32_e32 v189, 0xbfb8aa3b, v157
	v_mul_f32_e32 v190, 0xbfb8aa3b, v158
	v_mul_f32_e32 v191, 0xbfb8aa3b, v159
	v_exp_f32_e32 v164, v164
	v_exp_f32_e32 v165, v165
	v_exp_f32_e32 v166, v166
	v_exp_f32_e32 v167, v167
	v_exp_f32_e32 v172, v172
	v_exp_f32_e32 v173, v173
	v_exp_f32_e32 v174, v174
	v_exp_f32_e32 v175, v175
	v_exp_f32_e32 v180, v180
	v_exp_f32_e32 v181, v181
	v_exp_f32_e32 v182, v182
	v_exp_f32_e32 v183, v183
	v_exp_f32_e32 v188, v188
	v_exp_f32_e32 v189, v189
	v_exp_f32_e32 v190, v190
	v_exp_f32_e32 v191, v191
	s_nop 0
	v_add_f32_e32 v164, 1.0, v164
	v_add_f32_e32 v165, 1.0, v165
	v_add_f32_e32 v166, 1.0, v166
	v_add_f32_e32 v167, 1.0, v167
	v_add_f32_e32 v172, 1.0, v172
	v_add_f32_e32 v173, 1.0, v173
	v_add_f32_e32 v174, 1.0, v174
	v_add_f32_e32 v175, 1.0, v175
	v_add_f32_e32 v180, 1.0, v180
	v_add_f32_e32 v181, 1.0, v181
	v_add_f32_e32 v182, 1.0, v182
	v_add_f32_e32 v183, 1.0, v183
	v_add_f32_e32 v188, 1.0, v188
	v_add_f32_e32 v189, 1.0, v189
	v_add_f32_e32 v190, 1.0, v190
	v_add_f32_e32 v191, 1.0, v191
	v_rcp_f32_e32 v164, v164
	v_rcp_f32_e32 v165, v165
	v_rcp_f32_e32 v166, v166
	v_rcp_f32_e32 v167, v167
	v_rcp_f32_e32 v172, v172
	v_rcp_f32_e32 v173, v173
	v_rcp_f32_e32 v174, v174
	v_rcp_f32_e32 v175, v175
	v_rcp_f32_e32 v180, v180
	v_rcp_f32_e32 v181, v181
	v_rcp_f32_e32 v182, v182
	v_rcp_f32_e32 v183, v183
	v_rcp_f32_e32 v188, v188
	v_rcp_f32_e32 v189, v189
	v_rcp_f32_e32 v190, v190
	v_rcp_f32_e32 v191, v191
	s_nop 0
	v_mul_f32_e32 v200, v200, v132
	v_mul_f32_e32 v201, v201, v133
	v_mul_f32_e32 v202, v202, v134
	v_mul_f32_e32 v203, v203, v135
	v_mul_f32_e32 v204, v204, v140
	v_mul_f32_e32 v205, v205, v141
	v_mul_f32_e32 v206, v206, v142
	v_mul_f32_e32 v207, v207, v143
	v_mul_f32_e32 v208, v208, v148
	v_mul_f32_e32 v209, v209, v149
	v_mul_f32_e32 v210, v210, v150
	v_mul_f32_e32 v211, v211, v151
	v_mul_f32_e32 v212, v212, v156
	v_mul_f32_e32 v213, v213, v157
	v_mul_f32_e32 v214, v214, v158
	v_mul_f32_e32 v215, v215, v159
	v_mul_f32_e32 v200, v200, v164
	v_mul_f32_e32 v201, v201, v165
	v_mul_f32_e32 v202, v202, v166
	v_mul_f32_e32 v203, v203, v167
	v_mul_f32_e32 v204, v204, v172
	v_mul_f32_e32 v205, v205, v173
	v_mul_f32_e32 v206, v206, v174
	v_mul_f32_e32 v207, v207, v175
	v_mul_f32_e32 v208, v208, v180
	v_mul_f32_e32 v209, v209, v181
	v_mul_f32_e32 v210, v210, v182
	v_mul_f32_e32 v211, v211, v183
	v_mul_f32_e32 v212, v212, v188
	v_mul_f32_e32 v213, v213, v189
	v_mul_f32_e32 v214, v214, v190
	v_mul_f32_e32 v215, v215, v191
	v_cvt_pk_bf16_f32 v200, v200, v201
	v_cvt_pk_bf16_f32 v201, v202, v203
	v_cvt_pk_bf16_f32 v204, v204, v205
	v_cvt_pk_bf16_f32 v205, v206, v207
	v_cvt_pk_bf16_f32 v208, v208, v209
	v_cvt_pk_bf16_f32 v209, v210, v211
	v_cvt_pk_bf16_f32 v212, v212, v213
	v_cvt_pk_bf16_f32 v213, v214, v215
	buffer_store_dwordx2 v[200:201], v228, s[64:67], s84 offen offset:0
	buffer_store_dwordx2 v[204:205], v228, s[64:67], s84 offen offset:32
	buffer_store_dwordx2 v[208:209], v228, s[64:67], s84 offen offset:64
	buffer_store_dwordx2 v[212:213], v228, s[64:67], s84 offen offset:96
	s_add_u32 s16, s16, 1
	s_cmp_lt_u32 s16, 4
	s_cbranch_scc1 .Lmy_nat_qt
	s_add_u32 s0, s0, 1
	s_sub_u32 s89, s89, 1
	s_cmp_lg_u32 s89, 0
	s_cbranch_scc1 .Lmy_nat_item
; #define NEXT_ITEM() (MIX ? (int)__builtin_amdgcn_readfirstlane(lane == 0 ? __hip_atomic_fetch_add(qctr, 1u, __ATOMIC_RELAXED, __HIP_MEMORY_SCOPE_AGENT) : 0u) : item + (int)gridDim.x * 8)
; #define MKR(ptr) __builtin_amdgcn_make_buffer_rsrc((void*)(ptr), 0, 0x7fffffff, 0x00027000)
; template <bool MIX> __device__ __forceinline__ void scan_pass1(const Params& p, int d, float* ldsf) {
;     const int lane = threadIdx.x & 63, wid = __builtin_amdgcn_readfirstlane(threadIdx.x >> 6); const unsigned lo16 = (lane & 15) * 16, lo2 = lane * 2;
;     const float* Wd = (const float*)(p.ws + O_KD); const float* Bd = (const float*)(p.ws + O_Y); const u16* KB = (const u16*)(p.ws + O_K); const float* A = (const float*)(p.ws + O_A);
;     const u16* V = (const u16*)(p.ws + O_V); float* PT = (float*)(p.ws + O_PT); float* SLT = (float*)(p.ws + O_SLT); const unsigned lo8 = (lane & 15) * 8;
;     constexpr int NS = 32 * (NC - 1);
;     unsigned* qctr = (unsigned*)(p.ws + O_BAR);
;     if (MIX && wid >= 4) nat_phase(p, ldsf, blockIdx.x * 4 + (wid - 4), gridDim.x * 4);
;     ...
;     for (int item = MIX ? NEXT_ITEM() : (int)(blockIdx.x * 8 + wid); item < 2 * NS; item = NEXT_ITEM()) {
;         const bool isP = item >= NS; const int idx = isP ? item - NS : item;
;         const int bh = idx / (NC - 1), c = idx - bh * (NC - 1), b = bh >> 4, h = bh & 15;
;         const int t0 = d ? (SEQ - 1 - c * LC) : c * LC;
;         const size_t off0 = ((size_t)(b * SEQ + t0)) * RW + h * 64; const long stp = d ? -(long)RW : (long)RW;
;         const unsigned ob4 = (unsigned)(off0 * 4), ob2 = (unsigned)(off0 * 2);
;         const f32x4 ka4 = *(const f32x4*)(p.k_a + h * 64 + (lane & 15) * 4), c04 = 1.0f - ka4;
;         float S[64]; int ln = lane; asm volatile("" : "+v"(ln));
;     ...
;         const __amdgpu_buffer_rsrc_t rW = MKR(Wd), rA = MKR(A), rB = MKR(Bd), rK = MKR(KB), rV = MKR(V);
.Lmy_nat_next:
	s_add_i32 s88, s88, s81
	s_cmpk_lt_i32 s88, 0x1000
	s_cbranch_scc1 .Lmy_nat_pair
.Lmy_nat_end:
.LBB0_555:
	s_barrier
	s_mov_b64 exec, -1
	s_setprio 0
	v_readfirstlane_b32 s0, v254
	s_nop 3
	s_lshr_b32 s1, s0, 6
	s_lshl_b32 s0, s2, 3
	s_add_i32 s0, s1, s0
	s_mov_b32 s64, s56
	s_and_b32 s65, s57, 0xffff
	s_brev_b32 s66, -2
	s_mov_b32 s67, 0x27000
	s_mov_b32 s68, s54
	s_and_b32 s69, s55, 0xffff
	s_mov_b32 s70, s66
	s_mov_b32 s71, s67
	v_and_b32_e32 v212, 63, v254
	v_and_b32_e32 v213, 15, v254
	v_lshlrev_b32_e32 v204, 4, v213
	v_lshlrev_b32_e32 v205, 3, v213
	v_lshlrev_b32_e32 v206, 1, v212
	v_lshlrev_b32_e32 v207, 2, v212
	v_lshlrev_b32_e32 v210, 8, v212
	s_lshl_b32 s3, s1, 10
	s_add_u32 s3, s3, 0x10000
	v_add_u32_e32 v208, s3, v204
	v_and_b32_e32 v209, 3, v254
	v_lshlrev_b32_e32 v209, 2, v209
	v_add_u32_e32 v209, s3, v209
	v_mov_b32_e32 v213, 1.0
	v_mov_b32_e32 v214, 0
	v_mov_b32_e32 v215, 1
	s_mov_b64 exec, 1
	global_atomic_add v214, v214, v215, s[34:35] sc0
	s_mov_b64 exec, -1
	s_waitcnt vmcnt(0)
	s_nop 0
	v_readfirstlane_b32 s0, v214
	s_nop 3
